# coalesced-row GEMM staging + both 6-load segments split 4/4
# speedup vs baseline: 1.0068x; 1.0068x over previous
; #define PG8_STAGE(bufoff, gbase, voff) do { _Pragma("unroll") for (int _i = 0; _i < 2; ++_i) \
;         __builtin_amdgcn_global_load_lds((const unsigned*)((const char*)(gbase) + (voff)[_i]), (PG8_LAS unsigned*)(lds + (bufoff) + ldsw + _i * 8192), 16, 0, 0); } while (0)
; #define PG8_LDA(dst, b, h) do { _Pragma("unroll") for (int m = 0; m < 4; ++m) _Pragma("unroll") for (int k = 0; k < 2; ++k) dst[m][k] = *(const PG8_LAS bf16x8*)(lds + PG8_SA(b, h) + aoff + m * 2048 + k * 1024); } while (0)
; #define PG8_LDB(dst, b, h) do { _Pragma("unroll") for (int n = 0; n < 2; ++n) _Pragma("unroll") for (int k = 0; k < 2; ++k) dst[n][k] = *(const PG8_LAS bf16x8*)(lds + PG8_SB(b, h) + boff + n * 2048 + k * 1024); } while (0)
; #define PG8_MMA(ai, bj, At, Bt) do { __builtin_amdgcn_s_setprio(1); _Pragma("unroll") for (int m = 0; m < 4; ++m) _Pragma("unroll") for (int n = 0; n < 2; ++n) _Pragma("unroll") for (int k = 0; k < 2; ++k) \
;         acc[ai][bj][m][n] = __builtin_amdgcn_mfma_f32_16x16x32_bf16(Bt[n][k], At[m][k], acc[ai][bj][m][n], 0, 0, 0); __builtin_amdgcn_s_setprio(0); } while (0)
; #define PG8_WAIT_V(n) asm volatile("s_waitcnt vmcnt(" #n ")" ::: "memory")
; #define PG8_WAIT_L(n) asm volatile("s_waitcnt lgkmcnt(" #n ")" ::: "memory")
; #define PG8_BAR __builtin_amdgcn_s_barrier()
; #define PG8_SCHED __builtin_amdgcn_sched_barrier(0)
; template <class Epi, class Sched, bool ALIGN_EPI = false, bool SP2 = false>
; __device__ __forceinline__ void gemm_phase(PG8_LAS unsigned char* lds, const Gemm g, const Sched& S, const Epi& E) {
;     ...
;             PG8_LDB(B0, 0, 0); PG8_LDB(B1, 0, 1); PG8_SCHED; PG8_LDA(At, 0, 0); PG8_STAGE(PG8_SA(1, 1), a1 + hstep, voffA);
;             PG8_WAIT_V(8); PG8_WAIT_L(0); PG8_BAR; PG8_MMA(0, 0, At, B0); PG8_MMA(0, 1, At, B1); PG8_BAR; PG8_SCHED;
;             PG8_LDA(At, 0, 1); PG8_STAGE(PG8_SB(0, 0), b2, voffB); PG8_STAGE(PG8_SB(0, 1), b2 + hstep, voffB); PG8_STAGE(PG8_SA(0, 0), a2, voffA);
;             PG8_WAIT_V(8); PG8_WAIT_L(0); PG8_BAR; PG8_MMA(1, 0, At, B0); PG8_MMA(1, 1, At, B1); PG8_BAR; PG8_SCHED;
.LBB0_124:
	ds_read_b128 v[150:153], v161
	ds_read_b128 v[154:157], v223
	ds_read_b128 v[166:169], v161 offset:2048
	ds_read_b128 v[170:173], v223 offset:2048
	ds_read_b128 v[174:177], v162
	ds_read_b128 v[178:181], v224
	ds_read_b128 v[182:185], v162 offset:2048
	ds_read_b128 v[186:189], v224 offset:2048
	s_add_u32 s4, s36, 0xfff80080
	s_addc_u32 s5, s37, -1
	s_cmp_eq_u32 s69, 28
	s_cselect_b32 s41, s9, s5
	s_cselect_b32 s40, s27, s4
	s_cselect_b32 s39, s25, s68
	s_cselect_b32 s38, s35, s67
	s_add_i32 m0, s58, 0x80
	s_nop 0
	global_load_lds_dwordx4 v130, s[4:5] offset:-128
	s_add_i32 m0, s59, 0x80
	s_nop 0
	global_load_lds_dwordx4 v134, s[4:5] offset:-128
	s_add_i32 m0, s49, 0xc000
	ds_read_b128 v[190:193], v163
	ds_read_b128 v[194:197], v222
	ds_read_b128 v[198:201], v163 offset:2048
	ds_read_b128 v[202:205], v222 offset:2048
	ds_read_b128 v[206:209], v163 offset:4096
	ds_read_b128 v[210:213], v222 offset:4096
	ds_read_b128 v[214:217], v163 offset:6144
	ds_read_b128 v[218:221], v222 offset:6144
	global_load_lds_dwordx4 v140, s[36:37]
	s_add_i32 m0, s49, 0xe000
	s_nop 0
	global_load_lds_dwordx4 v142, s[36:37]
	s_waitcnt vmcnt(8)
	s_waitcnt lgkmcnt(0)
	s_barrier
	s_setprio 1
	s_waitcnt lgkmcnt(0)
	v_mfma_f32_16x16x32_bf16 v[126:129], v[150:153], v[190:193], v[126:129]
	v_mfma_f32_16x16x32_bf16 v[122:125], v[166:169], v[190:193], v[122:125]
	v_mfma_f32_16x16x32_bf16 v[110:113], v[150:153], v[198:201], v[110:113]
	v_mfma_f32_16x16x32_bf16 v[106:109], v[166:169], v[198:201], v[106:109]
	v_mfma_f32_16x16x32_bf16 v[94:97], v[150:153], v[206:209], v[94:97]
	v_mfma_f32_16x16x32_bf16 v[90:93], v[166:169], v[206:209], v[90:93]
	v_mfma_f32_16x16x32_bf16 v[78:81], v[150:153], v[214:217], v[78:81]
	v_mfma_f32_16x16x32_bf16 v[74:77], v[166:169], v[214:217], v[74:77]
	v_mfma_f32_16x16x32_bf16 v[126:129], v[154:157], v[194:197], v[126:129]
	v_mfma_f32_16x16x32_bf16 v[122:125], v[170:173], v[194:197], v[122:125]
	v_mfma_f32_16x16x32_bf16 v[110:113], v[154:157], v[202:205], v[110:113]
	v_mfma_f32_16x16x32_bf16 v[106:109], v[170:173], v[202:205], v[106:109]
	v_mfma_f32_16x16x32_bf16 v[94:97], v[154:157], v[210:213], v[94:97]
	v_mfma_f32_16x16x32_bf16 v[90:93], v[170:173], v[210:213], v[90:93]
	v_mfma_f32_16x16x32_bf16 v[78:81], v[154:157], v[218:221], v[78:81]
	v_mfma_f32_16x16x32_bf16 v[74:77], v[170:173], v[218:221], v[74:77]
	s_setprio 0
	s_setprio 1
	v_mfma_f32_16x16x32_bf16 v[118:121], v[174:177], v[190:193], v[118:121]
	v_mfma_f32_16x16x32_bf16 v[114:117], v[182:185], v[190:193], v[114:117]
	v_mfma_f32_16x16x32_bf16 v[102:105], v[174:177], v[198:201], v[102:105]
	v_mfma_f32_16x16x32_bf16 v[98:101], v[182:185], v[198:201], v[98:101]
	v_mfma_f32_16x16x32_bf16 v[86:89], v[174:177], v[206:209], v[86:89]
	v_mfma_f32_16x16x32_bf16 v[82:85], v[182:185], v[206:209], v[82:85]
	v_mfma_f32_16x16x32_bf16 v[70:73], v[174:177], v[214:217], v[70:73]
	v_mfma_f32_16x16x32_bf16 v[66:69], v[182:185], v[214:217], v[66:69]
	v_mfma_f32_16x16x32_bf16 v[118:121], v[178:181], v[194:197], v[118:121]
	v_mfma_f32_16x16x32_bf16 v[114:117], v[186:189], v[194:197], v[114:117]
	v_mfma_f32_16x16x32_bf16 v[102:105], v[178:181], v[202:205], v[102:105]
	v_mfma_f32_16x16x32_bf16 v[98:101], v[186:189], v[202:205], v[98:101]
	v_mfma_f32_16x16x32_bf16 v[86:89], v[178:181], v[210:213], v[86:89]
	v_mfma_f32_16x16x32_bf16 v[82:85], v[186:189], v[210:213], v[82:85]
	v_mfma_f32_16x16x32_bf16 v[70:73], v[178:181], v[218:221], v[70:73]
	v_mfma_f32_16x16x32_bf16 v[66:69], v[186:189], v[218:221], v[66:69]
	s_setprio 0
	s_barrier
	s_add_i32 s4, s64, s48
	s_mov_b32 m0, s4
	ds_read_b128 v[190:193], v163 offset:16384
	ds_read_b128 v[194:197], v222 offset:16384
	ds_read_b128 v[198:201], v163 offset:18432
	ds_read_b128 v[202:205], v222 offset:18432
	ds_read_b128 v[206:209], v163 offset:20480
	ds_read_b128 v[210:213], v222 offset:20480
	ds_read_b128 v[214:217], v163 offset:22528
	ds_read_b128 v[218:221], v222 offset:22528
	global_load_lds_dwordx4 v132, s[38:39]
	s_add_i32 m0, s4, 0x2000
	s_add_u32 s70, s38, 0x80000
	s_addc_u32 s71, s39, 0
	s_add_i32 s4, s65, s48
	global_load_lds_dwordx4 v136, s[38:39]
	s_mov_b32 m0, s4
	s_nop 0
	global_load_lds_dwordx4 v132, s[70:71]
	s_add_i32 m0, s4, 0x2000
	s_nop 0
	global_load_lds_dwordx4 v136, s[70:71]
	s_waitcnt vmcnt(6)
	s_waitcnt lgkmcnt(0)
	s_barrier
	s_setprio 1
	s_waitcnt lgkmcnt(0)
	v_mfma_f32_16x16x32_bf16 v[62:65], v[150:153], v[190:193], v[62:65]
	v_mfma_f32_16x16x32_bf16 v[58:61], v[166:169], v[190:193], v[58:61]
	v_mfma_f32_16x16x32_bf16 v[46:49], v[150:153], v[198:201], v[46:49]
	v_mfma_f32_16x16x32_bf16 v[42:45], v[166:169], v[198:201], v[42:45]
	v_mfma_f32_16x16x32_bf16 v[30:33], v[150:153], v[206:209], v[30:33]
	v_mfma_f32_16x16x32_bf16 v[26:29], v[166:169], v[206:209], v[26:29]
	v_mfma_f32_16x16x32_bf16 v[14:17], v[150:153], v[214:217], v[14:17]
	v_mfma_f32_16x16x32_bf16 v[10:13], v[166:169], v[214:217], v[10:13]
	v_mfma_f32_16x16x32_bf16 v[62:65], v[154:157], v[194:197], v[62:65]
	v_mfma_f32_16x16x32_bf16 v[58:61], v[170:173], v[194:197], v[58:61]
	v_mfma_f32_16x16x32_bf16 v[46:49], v[154:157], v[202:205], v[46:49]
	v_mfma_f32_16x16x32_bf16 v[42:45], v[170:173], v[202:205], v[42:45]
	v_mfma_f32_16x16x32_bf16 v[30:33], v[154:157], v[210:213], v[30:33]
	v_mfma_f32_16x16x32_bf16 v[26:29], v[170:173], v[210:213], v[26:29]
	v_mfma_f32_16x16x32_bf16 v[14:17], v[154:157], v[218:221], v[14:17]
	v_mfma_f32_16x16x32_bf16 v[10:13], v[170:173], v[218:221], v[10:13]
	s_setprio 0
	s_setprio 1
	v_mfma_f32_16x16x32_bf16 v[54:57], v[174:177], v[190:193], v[54:57]
	v_mfma_f32_16x16x32_bf16 v[50:53], v[182:185], v[190:193], v[50:53]
	v_mfma_f32_16x16x32_bf16 v[38:41], v[174:177], v[198:201], v[38:41]
	v_mfma_f32_16x16x32_bf16 v[34:37], v[182:185], v[198:201], v[34:37]
	v_mfma_f32_16x16x32_bf16 v[22:25], v[174:177], v[206:209], v[22:25]
	v_mfma_f32_16x16x32_bf16 v[18:21], v[182:185], v[206:209], v[18:21]
	v_mfma_f32_16x16x32_bf16 v[6:9], v[174:177], v[214:217], v[6:9]
	v_mfma_f32_16x16x32_bf16 v[2:5], v[182:185], v[214:217], v[2:5]
	v_mfma_f32_16x16x32_bf16 v[54:57], v[178:181], v[194:197], v[54:57]
	v_mfma_f32_16x16x32_bf16 v[50:53], v[186:189], v[194:197], v[50:53]
	v_mfma_f32_16x16x32_bf16 v[38:41], v[178:181], v[202:205], v[38:41]
	v_mfma_f32_16x16x32_bf16 v[34:37], v[186:189], v[202:205], v[34:37]
	v_mfma_f32_16x16x32_bf16 v[22:25], v[178:181], v[210:213], v[22:25]
	v_mfma_f32_16x16x32_bf16 v[18:21], v[186:189], v[210:213], v[18:21]
	v_mfma_f32_16x16x32_bf16 v[6:9], v[178:181], v[218:221], v[6:9]
	v_mfma_f32_16x16x32_bf16 v[2:5], v[186:189], v[218:221], v[2:5]
	s_setprio 0
	s_barrier
; #define PG8_STAGE(bufoff, gbase, voff) do { _Pragma("unroll") for (int _i = 0; _i < 2; ++_i) \
;         __builtin_amdgcn_global_load_lds((const unsigned*)((const char*)(gbase) + (voff)[_i]), (PG8_LAS unsigned*)(lds + (bufoff) + ldsw + _i * 8192), 16, 0, 0); } while (0)
; #define PG8_LDA(dst, b, h) do { _Pragma("unroll") for (int m = 0; m < 4; ++m) _Pragma("unroll") for (int k = 0; k < 2; ++k) dst[m][k] = *(const PG8_LAS bf16x8*)(lds + PG8_SA(b, h) + aoff + m * 2048 + k * 1024); } while (0)
; #define PG8_LDB(dst, b, h) do { _Pragma("unroll") for (int n = 0; n < 2; ++n) _Pragma("unroll") for (int k = 0; k < 2; ++k) dst[n][k] = *(const PG8_LAS bf16x8*)(lds + PG8_SB(b, h) + boff + n * 2048 + k * 1024); } while (0)
; #define PG8_MMA(ai, bj, At, Bt) do { __builtin_amdgcn_s_setprio(1); _Pragma("unroll") for (int m = 0; m < 4; ++m) _Pragma("unroll") for (int n = 0; n < 2; ++n) _Pragma("unroll") for (int k = 0; k < 2; ++k) \
;         acc[ai][bj][m][n] = __builtin_amdgcn_mfma_f32_16x16x32_bf16(Bt[n][k], At[m][k], acc[ai][bj][m][n], 0, 0, 0); __builtin_amdgcn_s_setprio(0); } while (0)
; #define PG8_WAIT_V(n) asm volatile("s_waitcnt vmcnt(" #n ")" ::: "memory")
; #define PG8_WAIT_L(n) asm volatile("s_waitcnt lgkmcnt(" #n ")" ::: "memory")
; #define PG8_BAR __builtin_amdgcn_s_barrier()
; template <class Epi, class Sched, bool ALIGN_EPI = false, bool SP2 = false>
; __device__ __forceinline__ void gemm_phase(PG8_LAS unsigned char* lds, const Gemm g, const Sched& S, const Epi& E) {
;     ...
;         for (int t = 0; t < nt; t += 2) {
;             const bool last = (t == nt - 2);
;             const char* a1 = cA + (size_t)(t + 1) * kstep;
;             const char* a2 = last ? nA : cA + (size_t)(t + 2) * kstep; const char* b2 = last ? nB : cB + (size_t)(t + 2) * kstep;
;             const char* a3 = a2 + kstep; const char* b3 = b2 + kstep;
;     ...
;             PG8_LDB(B0, 1, 0); PG8_LDB(B1, 1, 1); PG8_SCHED; PG8_LDA(At, 1, 0); PG8_STAGE(PG8_SA(0, 1), a2 + hstep, voffA);
;             PG8_WAIT_V(8); PG8_WAIT_L(0); PG8_BAR; PG8_MMA(0, 0, At, B0); PG8_MMA(0, 1, At, B1); PG8_BAR; PG8_SCHED;
;             PG8_LDA(At, 1, 1); PG8_STAGE(PG8_SB(1, 0), b3, voffB); PG8_STAGE(PG8_SB(1, 1), b3 + hstep, voffB); PG8_STAGE(PG8_SA(1, 0), a3, voffA);
;             PG8_WAIT_V(8); PG8_WAIT_L(0); PG8_BAR; PG8_MMA(1, 0, At, B0); PG8_MMA(1, 1, At, B1); PG8_BAR; PG8_SCHED;
	s_add_i32 s4, 0, 0x18000
	s_add_i32 s5, 0, 0x1c000
	ds_read_b128 v[150:153], v225
	ds_read_b128 v[154:157], v226
	ds_read_b128 v[166:169], v225 offset:2048
	ds_read_b128 v[170:173], v226 offset:2048
	ds_read_b128 v[174:177], v227
	ds_read_b128 v[178:181], v228
	ds_read_b128 v[182:185], v227 offset:2048
	ds_read_b128 v[186:189], v228 offset:2048
	s_add_u32 s70, s40, 0x80000
	s_addc_u32 s71, s41, 0
	s_mov_b32 m0, s49
	s_nop 0
	global_load_lds_dwordx4 v130, s[40:41]
	s_mov_b32 m0, s50
	s_nop 0
	global_load_lds_dwordx4 v134, s[40:41]
	s_mov_b32 m0, s51
	ds_read_b128 v[190:193], v163 offset:32768
	ds_read_b128 v[194:197], v222 offset:32768
	ds_read_b128 v[198:201], v163 offset:34816
	ds_read_b128 v[202:205], v222 offset:34816
	ds_read_b128 v[206:209], v163 offset:36864
	ds_read_b128 v[210:213], v222 offset:36864
	ds_read_b128 v[214:217], v163 offset:38912
	ds_read_b128 v[218:221], v222 offset:38912
	global_load_lds_dwordx4 v130, s[70:71]
	s_mov_b32 m0, s52
	s_nop 0
	global_load_lds_dwordx4 v134, s[70:71]
	s_waitcnt vmcnt(8)
	s_waitcnt lgkmcnt(0)
	s_barrier
	s_setprio 1
	s_waitcnt lgkmcnt(0)
	v_mfma_f32_16x16x32_bf16 v[126:129], v[150:153], v[190:193], v[126:129]
	v_mfma_f32_16x16x32_bf16 v[122:125], v[166:169], v[190:193], v[122:125]
	v_mfma_f32_16x16x32_bf16 v[110:113], v[150:153], v[198:201], v[110:113]
	v_mfma_f32_16x16x32_bf16 v[106:109], v[166:169], v[198:201], v[106:109]
	v_mfma_f32_16x16x32_bf16 v[94:97], v[150:153], v[206:209], v[94:97]
	v_mfma_f32_16x16x32_bf16 v[90:93], v[166:169], v[206:209], v[90:93]
	v_mfma_f32_16x16x32_bf16 v[78:81], v[150:153], v[214:217], v[78:81]
	v_mfma_f32_16x16x32_bf16 v[74:77], v[166:169], v[214:217], v[74:77]
	v_mfma_f32_16x16x32_bf16 v[126:129], v[154:157], v[194:197], v[126:129]
	v_mfma_f32_16x16x32_bf16 v[122:125], v[170:173], v[194:197], v[122:125]
	v_mfma_f32_16x16x32_bf16 v[110:113], v[154:157], v[202:205], v[110:113]
	v_mfma_f32_16x16x32_bf16 v[106:109], v[170:173], v[202:205], v[106:109]
	v_mfma_f32_16x16x32_bf16 v[94:97], v[154:157], v[210:213], v[94:97]
	v_mfma_f32_16x16x32_bf16 v[90:93], v[170:173], v[210:213], v[90:93]
	v_mfma_f32_16x16x32_bf16 v[78:81], v[154:157], v[218:221], v[78:81]
	v_mfma_f32_16x16x32_bf16 v[74:77], v[170:173], v[218:221], v[74:77]
	s_setprio 0
	s_setprio 1
	v_mfma_f32_16x16x32_bf16 v[118:121], v[174:177], v[190:193], v[118:121]
	v_mfma_f32_16x16x32_bf16 v[114:117], v[182:185], v[190:193], v[114:117]
	v_mfma_f32_16x16x32_bf16 v[102:105], v[174:177], v[198:201], v[102:105]
	v_mfma_f32_16x16x32_bf16 v[98:101], v[182:185], v[198:201], v[98:101]
	v_mfma_f32_16x16x32_bf16 v[86:89], v[174:177], v[206:209], v[86:89]
	v_mfma_f32_16x16x32_bf16 v[82:85], v[182:185], v[206:209], v[82:85]
	v_mfma_f32_16x16x32_bf16 v[70:73], v[174:177], v[214:217], v[70:73]
	v_mfma_f32_16x16x32_bf16 v[66:69], v[182:185], v[214:217], v[66:69]
	v_mfma_f32_16x16x32_bf16 v[118:121], v[178:181], v[194:197], v[118:121]
	v_mfma_f32_16x16x32_bf16 v[114:117], v[186:189], v[194:197], v[114:117]
	v_mfma_f32_16x16x32_bf16 v[102:105], v[178:181], v[202:205], v[102:105]
	v_mfma_f32_16x16x32_bf16 v[98:101], v[186:189], v[202:205], v[98:101]
	v_mfma_f32_16x16x32_bf16 v[86:89], v[178:181], v[210:213], v[86:89]
	v_mfma_f32_16x16x32_bf16 v[82:85], v[186:189], v[210:213], v[82:85]
	v_mfma_f32_16x16x32_bf16 v[70:73], v[178:181], v[218:221], v[70:73]
	v_mfma_f32_16x16x32_bf16 v[66:69], v[186:189], v[218:221], v[66:69]
	s_setprio 0
	s_barrier
	s_add_i32 s4, s4, s48
	s_add_i32 m0, s4, 0xffffff80
	ds_read_b128 v[190:193], v163 offset:49152
	ds_read_b128 v[194:197], v222 offset:49152
	ds_read_b128 v[198:201], v163 offset:51200
	ds_read_b128 v[202:205], v222 offset:51200
	ds_read_b128 v[206:209], v163 offset:53248
	ds_read_b128 v[210:213], v222 offset:53248
	ds_read_b128 v[214:217], v163 offset:55296
	ds_read_b128 v[218:221], v222 offset:55296
	global_load_lds_dwordx4 v132, s[38:39] offset:128
	s_add_i32 m0, s4, 0x1f80
	s_nop 0
	global_load_lds_dwordx4 v136, s[38:39] offset:128
	s_add_u32 s38, s38, 0x80080
	s_addc_u32 s39, s39, 0
	s_add_i32 s4, s5, s48
	s_mov_b32 m0, s4
	s_nop 0
	global_load_lds_dwordx4 v132, s[38:39]
	s_add_i32 m0, s4, 0x2000
	s_nop 0
	global_load_lds_dwordx4 v136, s[38:39]
	s_waitcnt vmcnt(6)
	s_waitcnt lgkmcnt(0)
	s_barrier
	s_setprio 1
	s_waitcnt lgkmcnt(0)
	v_mfma_f32_16x16x32_bf16 v[62:65], v[150:153], v[190:193], v[62:65]
	v_mfma_f32_16x16x32_bf16 v[58:61], v[166:169], v[190:193], v[58:61]
	v_mfma_f32_16x16x32_bf16 v[46:49], v[150:153], v[198:201], v[46:49]
	v_mfma_f32_16x16x32_bf16 v[42:45], v[166:169], v[198:201], v[42:45]
	v_mfma_f32_16x16x32_bf16 v[30:33], v[150:153], v[206:209], v[30:33]
	v_mfma_f32_16x16x32_bf16 v[26:29], v[166:169], v[206:209], v[26:29]
	v_mfma_f32_16x16x32_bf16 v[14:17], v[150:153], v[214:217], v[14:17]
	v_mfma_f32_16x16x32_bf16 v[10:13], v[166:169], v[214:217], v[10:13]
	v_mfma_f32_16x16x32_bf16 v[62:65], v[154:157], v[194:197], v[62:65]
	v_mfma_f32_16x16x32_bf16 v[58:61], v[170:173], v[194:197], v[58:61]
	v_mfma_f32_16x16x32_bf16 v[46:49], v[154:157], v[202:205], v[46:49]
	v_mfma_f32_16x16x32_bf16 v[42:45], v[170:173], v[202:205], v[42:45]
	v_mfma_f32_16x16x32_bf16 v[30:33], v[154:157], v[210:213], v[30:33]
	v_mfma_f32_16x16x32_bf16 v[26:29], v[170:173], v[210:213], v[26:29]
	v_mfma_f32_16x16x32_bf16 v[14:17], v[154:157], v[218:221], v[14:17]
	v_mfma_f32_16x16x32_bf16 v[10:13], v[170:173], v[218:221], v[10:13]
	s_setprio 0
	s_setprio 1
	v_mfma_f32_16x16x32_bf16 v[54:57], v[174:177], v[190:193], v[54:57]
	v_mfma_f32_16x16x32_bf16 v[50:53], v[182:185], v[190:193], v[50:53]
	v_mfma_f32_16x16x32_bf16 v[38:41], v[174:177], v[198:201], v[38:41]
	v_mfma_f32_16x16x32_bf16 v[34:37], v[182:185], v[198:201], v[34:37]
	v_mfma_f32_16x16x32_bf16 v[22:25], v[174:177], v[206:209], v[22:25]
	v_mfma_f32_16x16x32_bf16 v[18:21], v[182:185], v[206:209], v[18:21]
	v_mfma_f32_16x16x32_bf16 v[6:9], v[174:177], v[214:217], v[6:9]
	v_mfma_f32_16x16x32_bf16 v[2:5], v[182:185], v[214:217], v[2:5]
	v_mfma_f32_16x16x32_bf16 v[54:57], v[178:181], v[194:197], v[54:57]
	v_mfma_f32_16x16x32_bf16 v[50:53], v[186:189], v[194:197], v[50:53]
	v_mfma_f32_16x16x32_bf16 v[38:41], v[178:181], v[202:205], v[38:41]
	v_mfma_f32_16x16x32_bf16 v[34:37], v[186:189], v[202:205], v[34:37]
	v_mfma_f32_16x16x32_bf16 v[22:25], v[178:181], v[210:213], v[22:25]
	v_mfma_f32_16x16x32_bf16 v[18:21], v[186:189], v[210:213], v[18:21]
	v_mfma_f32_16x16x32_bf16 v[6:9], v[178:181], v[218:221], v[6:9]
	v_mfma_f32_16x16x32_bf16 v[2:5], v[186:189], v[218:221], v[2:5]
	s_setprio 0
	s_barrier
	s_add_i32 s69, s69, 2
	s_add_u32 s36, s36, 0x100
	s_addc_u32 s37, s37, 0
	s_add_u32 s67, s67, 0x100
	s_addc_u32 s68, s68, 0
	s_cmp_gt_u32 s69, 29
	s_cbranch_scc0 .LBB0_124
	s_and_b64 vcc, exec, s[22:23]
	s_cbranch_vccz .LBB0_127
	s_barrier

; #define PG8_STAGE(bufoff, gbase, voff) do { _Pragma("unroll") for (int _i = 0; _i < 2; ++_i) \
;         __builtin_amdgcn_global_load_lds((const unsigned*)((const char*)(gbase) + (voff)[_i]), (PG8_LAS unsigned*)(lds + (bufoff) + ldsw + _i * 8192), 16, 0, 0); } while (0)
; #define PG8_LDA(dst, b, h) do { _Pragma("unroll") for (int m = 0; m < 4; ++m) _Pragma("unroll") for (int k = 0; k < 2; ++k) dst[m][k] = *(const PG8_LAS bf16x8*)(lds + PG8_SA(b, h) + aoff + m * 2048 + k * 1024); } while (0)
; #define PG8_LDB(dst, b, h) do { _Pragma("unroll") for (int n = 0; n < 2; ++n) _Pragma("unroll") for (int k = 0; k < 2; ++k) dst[n][k] = *(const PG8_LAS bf16x8*)(lds + PG8_SB(b, h) + boff + n * 2048 + k * 1024); } while (0)
; #define PG8_MMA(ai, bj, At, Bt) do { __builtin_amdgcn_s_setprio(1); _Pragma("unroll") for (int m = 0; m < 4; ++m) _Pragma("unroll") for (int n = 0; n < 2; ++n) _Pragma("unroll") for (int k = 0; k < 2; ++k) \
;         acc[ai][bj][m][n] = __builtin_amdgcn_mfma_f32_16x16x32_bf16(Bt[n][k], At[m][k], acc[ai][bj][m][n], 0, 0, 0); __builtin_amdgcn_s_setprio(0); } while (0)
; #define PG8_WAIT_V(n) asm volatile("s_waitcnt vmcnt(" #n ")" ::: "memory")
; #define PG8_WAIT_L(n) asm volatile("s_waitcnt lgkmcnt(" #n ")" ::: "memory")
; #define PG8_BAR __builtin_amdgcn_s_barrier()
; #define PG8_SCHED __builtin_amdgcn_sched_barrier(0)
; template <class Epi, class Sched, bool ALIGN_EPI = false, bool SP2 = false>
; __device__ __forceinline__ void gemm_phase(PG8_LAS unsigned char* lds, const Gemm g, const Sched& S, const Epi& E) {
;     ...
;             PG8_LDB(B0, 0, 0); PG8_LDB(B1, 0, 1); PG8_SCHED; PG8_LDA(At, 0, 0); PG8_STAGE(PG8_SA(1, 1), a1 + hstep, voffA);
;             PG8_WAIT_V(8); PG8_WAIT_L(0); PG8_BAR; PG8_MMA(0, 0, At, B0); PG8_MMA(0, 1, At, B1); PG8_BAR; PG8_SCHED;
;             PG8_LDA(At, 0, 1); PG8_STAGE(PG8_SB(0, 0), b2, voffB); PG8_STAGE(PG8_SB(0, 1), b2 + hstep, voffB); PG8_STAGE(PG8_SA(0, 0), a2, voffA);
;             PG8_WAIT_V(8); PG8_WAIT_L(0); PG8_BAR; PG8_MMA(1, 0, At, B0); PG8_MMA(1, 1, At, B1); PG8_BAR; PG8_SCHED;
.LBB0_763:
	ds_read_b128 v[154:157], v150
	ds_read_b128 v[158:161], v147
	ds_read_b128 v[162:165], v150 offset:2048
	ds_read_b128 v[166:169], v147 offset:2048
	ds_read_b128 v[170:173], v151
	ds_read_b128 v[174:177], v218
	ds_read_b128 v[178:181], v151 offset:2048
	ds_read_b128 v[182:185], v218 offset:2048
	s_add_u32 s4, s40, 0xfff80080
	s_addc_u32 s5, s41, -1
	s_cmp_eq_u32 s78, 28
	s_cselect_b32 s51, s31, s5
	s_cselect_b32 s50, s74, s4
	s_cselect_b32 s49, s29, s77
	s_cselect_b32 s48, s75, s76
	s_add_i32 m0, s63, 0x80
	s_nop 0
	global_load_lds_dwordx4 v130, s[4:5] offset:-128
	s_add_i32 m0, s64, 0x80
	s_nop 0
	global_load_lds_dwordx4 v134, s[4:5] offset:-128
	s_add_i32 m0, s39, 0xc000
	ds_read_b128 v[186:189], v152
	ds_read_b128 v[190:193], v146
	ds_read_b128 v[194:197], v152 offset:2048
	ds_read_b128 v[198:201], v146 offset:2048
	ds_read_b128 v[202:205], v152 offset:4096
	ds_read_b128 v[206:209], v146 offset:4096
	ds_read_b128 v[210:213], v152 offset:6144
	ds_read_b128 v[214:217], v146 offset:6144
	global_load_lds_dwordx4 v138, s[40:41]
	s_add_i32 m0, s39, 0xe000
	s_nop 0
	global_load_lds_dwordx4 v140, s[40:41]
	s_waitcnt vmcnt(8)
	s_waitcnt lgkmcnt(0)
	s_barrier
	s_setprio 1
	s_waitcnt lgkmcnt(0)
	v_mfma_f32_16x16x32_bf16 v[126:129], v[154:157], v[186:189], v[126:129]
	v_mfma_f32_16x16x32_bf16 v[122:125], v[162:165], v[186:189], v[122:125]
	v_mfma_f32_16x16x32_bf16 v[114:117], v[154:157], v[194:197], v[114:117]
	v_mfma_f32_16x16x32_bf16 v[106:109], v[162:165], v[194:197], v[106:109]
	v_mfma_f32_16x16x32_bf16 v[98:101], v[154:157], v[202:205], v[98:101]
	v_mfma_f32_16x16x32_bf16 v[90:93], v[162:165], v[202:205], v[90:93]
	v_mfma_f32_16x16x32_bf16 v[82:85], v[154:157], v[210:213], v[82:85]
	v_mfma_f32_16x16x32_bf16 v[74:77], v[162:165], v[210:213], v[74:77]
	v_mfma_f32_16x16x32_bf16 v[126:129], v[158:161], v[190:193], v[126:129]
	v_mfma_f32_16x16x32_bf16 v[122:125], v[166:169], v[190:193], v[122:125]
	v_mfma_f32_16x16x32_bf16 v[114:117], v[158:161], v[198:201], v[114:117]
	v_mfma_f32_16x16x32_bf16 v[106:109], v[166:169], v[198:201], v[106:109]
	v_mfma_f32_16x16x32_bf16 v[98:101], v[158:161], v[206:209], v[98:101]
	v_mfma_f32_16x16x32_bf16 v[90:93], v[166:169], v[206:209], v[90:93]
	v_mfma_f32_16x16x32_bf16 v[82:85], v[158:161], v[214:217], v[82:85]
	v_mfma_f32_16x16x32_bf16 v[74:77], v[166:169], v[214:217], v[74:77]
	s_setprio 0
	s_setprio 1
	v_mfma_f32_16x16x32_bf16 v[118:121], v[170:173], v[186:189], v[118:121]
	v_mfma_f32_16x16x32_bf16 v[110:113], v[178:181], v[186:189], v[110:113]
	v_mfma_f32_16x16x32_bf16 v[102:105], v[170:173], v[194:197], v[102:105]
	v_mfma_f32_16x16x32_bf16 v[94:97], v[178:181], v[194:197], v[94:97]
	v_mfma_f32_16x16x32_bf16 v[86:89], v[170:173], v[202:205], v[86:89]
	v_mfma_f32_16x16x32_bf16 v[78:81], v[178:181], v[202:205], v[78:81]
	v_mfma_f32_16x16x32_bf16 v[70:73], v[170:173], v[210:213], v[70:73]
	v_mfma_f32_16x16x32_bf16 v[66:69], v[178:181], v[210:213], v[66:69]
	v_mfma_f32_16x16x32_bf16 v[118:121], v[174:177], v[190:193], v[118:121]
	v_mfma_f32_16x16x32_bf16 v[110:113], v[182:185], v[190:193], v[110:113]
	v_mfma_f32_16x16x32_bf16 v[102:105], v[174:177], v[198:201], v[102:105]
	v_mfma_f32_16x16x32_bf16 v[94:97], v[182:185], v[198:201], v[94:97]
	v_mfma_f32_16x16x32_bf16 v[86:89], v[174:177], v[206:209], v[86:89]
	v_mfma_f32_16x16x32_bf16 v[78:81], v[182:185], v[206:209], v[78:81]
	v_mfma_f32_16x16x32_bf16 v[70:73], v[174:177], v[214:217], v[70:73]
	v_mfma_f32_16x16x32_bf16 v[66:69], v[182:185], v[214:217], v[66:69]
	s_setprio 0
	s_barrier
	s_add_i32 s4, s67, s58
	s_mov_b32 m0, s4
	ds_read_b128 v[186:189], v152 offset:16384
	ds_read_b128 v[190:193], v146 offset:16384
	ds_read_b128 v[194:197], v152 offset:18432
	ds_read_b128 v[198:201], v146 offset:18432
	ds_read_b128 v[202:205], v152 offset:20480
	ds_read_b128 v[206:209], v146 offset:20480
	ds_read_b128 v[210:213], v152 offset:22528
	ds_read_b128 v[214:217], v146 offset:22528
	global_load_lds_dwordx4 v132, s[48:49]
	s_add_i32 m0, s4, 0x2000
	s_add_u32 s4, s48, 0x80000
	s_addc_u32 s5, s49, 0
	s_add_i32 s79, s68, s58
	global_load_lds_dwordx4 v136, s[48:49]
	s_mov_b32 m0, s79
	s_nop 0
	global_load_lds_dwordx4 v132, s[4:5]
	s_add_i32 m0, s79, 0x2000
	s_nop 0
	global_load_lds_dwordx4 v136, s[4:5]
	s_waitcnt vmcnt(6)
	s_waitcnt lgkmcnt(0)
	s_barrier
	s_setprio 1
	s_waitcnt lgkmcnt(0)
	v_mfma_f32_16x16x32_bf16 v[62:65], v[154:157], v[186:189], v[62:65]
	v_mfma_f32_16x16x32_bf16 v[58:61], v[162:165], v[186:189], v[58:61]
	v_mfma_f32_16x16x32_bf16 v[50:53], v[154:157], v[194:197], v[50:53]
	v_mfma_f32_16x16x32_bf16 v[42:45], v[162:165], v[194:197], v[42:45]
	v_mfma_f32_16x16x32_bf16 v[34:37], v[154:157], v[202:205], v[34:37]
	v_mfma_f32_16x16x32_bf16 v[26:29], v[162:165], v[202:205], v[26:29]
	v_mfma_f32_16x16x32_bf16 v[18:21], v[154:157], v[210:213], v[18:21]
	v_mfma_f32_16x16x32_bf16 v[10:13], v[162:165], v[210:213], v[10:13]
	v_mfma_f32_16x16x32_bf16 v[62:65], v[158:161], v[190:193], v[62:65]
	v_mfma_f32_16x16x32_bf16 v[58:61], v[166:169], v[190:193], v[58:61]
	v_mfma_f32_16x16x32_bf16 v[50:53], v[158:161], v[198:201], v[50:53]
	v_mfma_f32_16x16x32_bf16 v[42:45], v[166:169], v[198:201], v[42:45]
	v_mfma_f32_16x16x32_bf16 v[34:37], v[158:161], v[206:209], v[34:37]
	v_mfma_f32_16x16x32_bf16 v[26:29], v[166:169], v[206:209], v[26:29]
	v_mfma_f32_16x16x32_bf16 v[18:21], v[158:161], v[214:217], v[18:21]
	v_mfma_f32_16x16x32_bf16 v[10:13], v[166:169], v[214:217], v[10:13]
	s_setprio 0
	s_setprio 1
	v_mfma_f32_16x16x32_bf16 v[54:57], v[170:173], v[186:189], v[54:57]
	v_mfma_f32_16x16x32_bf16 v[46:49], v[178:181], v[186:189], v[46:49]
	v_mfma_f32_16x16x32_bf16 v[38:41], v[170:173], v[194:197], v[38:41]
	v_mfma_f32_16x16x32_bf16 v[30:33], v[178:181], v[194:197], v[30:33]
	v_mfma_f32_16x16x32_bf16 v[22:25], v[170:173], v[202:205], v[22:25]
	v_mfma_f32_16x16x32_bf16 v[14:17], v[178:181], v[202:205], v[14:17]
	v_mfma_f32_16x16x32_bf16 v[6:9], v[170:173], v[210:213], v[6:9]
	v_mfma_f32_16x16x32_bf16 v[2:5], v[178:181], v[210:213], v[2:5]
	v_mfma_f32_16x16x32_bf16 v[54:57], v[174:177], v[190:193], v[54:57]
	v_mfma_f32_16x16x32_bf16 v[46:49], v[182:185], v[190:193], v[46:49]
	v_mfma_f32_16x16x32_bf16 v[38:41], v[174:177], v[198:201], v[38:41]
	v_mfma_f32_16x16x32_bf16 v[30:33], v[182:185], v[198:201], v[30:33]
	v_mfma_f32_16x16x32_bf16 v[22:25], v[174:177], v[206:209], v[22:25]
	v_mfma_f32_16x16x32_bf16 v[14:17], v[182:185], v[206:209], v[14:17]
	v_mfma_f32_16x16x32_bf16 v[6:9], v[174:177], v[214:217], v[6:9]
	v_mfma_f32_16x16x32_bf16 v[2:5], v[182:185], v[214:217], v[2:5]
	s_setprio 0
	s_barrier
; #define PG8_STAGE(bufoff, gbase, voff) do { _Pragma("unroll") for (int _i = 0; _i < 2; ++_i) \
;         __builtin_amdgcn_global_load_lds((const unsigned*)((const char*)(gbase) + (voff)[_i]), (PG8_LAS unsigned*)(lds + (bufoff) + ldsw + _i * 8192), 16, 0, 0); } while (0)
; #define PG8_LDA(dst, b, h) do { _Pragma("unroll") for (int m = 0; m < 4; ++m) _Pragma("unroll") for (int k = 0; k < 2; ++k) dst[m][k] = *(const PG8_LAS bf16x8*)(lds + PG8_SA(b, h) + aoff + m * 2048 + k * 1024); } while (0)
; #define PG8_LDB(dst, b, h) do { _Pragma("unroll") for (int n = 0; n < 2; ++n) _Pragma("unroll") for (int k = 0; k < 2; ++k) dst[n][k] = *(const PG8_LAS bf16x8*)(lds + PG8_SB(b, h) + boff + n * 2048 + k * 1024); } while (0)
; #define PG8_MMA(ai, bj, At, Bt) do { __builtin_amdgcn_s_setprio(1); _Pragma("unroll") for (int m = 0; m < 4; ++m) _Pragma("unroll") for (int n = 0; n < 2; ++n) _Pragma("unroll") for (int k = 0; k < 2; ++k) \
;         acc[ai][bj][m][n] = __builtin_amdgcn_mfma_f32_16x16x32_bf16(Bt[n][k], At[m][k], acc[ai][bj][m][n], 0, 0, 0); __builtin_amdgcn_s_setprio(0); } while (0)
; #define PG8_WAIT_V(n) asm volatile("s_waitcnt vmcnt(" #n ")" ::: "memory")
; #define PG8_WAIT_L(n) asm volatile("s_waitcnt lgkmcnt(" #n ")" ::: "memory")
; #define PG8_BAR __builtin_amdgcn_s_barrier()
; template <class Epi, class Sched, bool ALIGN_EPI = false, bool SP2 = false>
; __device__ __forceinline__ void gemm_phase(PG8_LAS unsigned char* lds, const Gemm g, const Sched& S, const Epi& E) {
;     ...
;         for (int t = 0; t < nt; t += 2) {
;             const bool last = (t == nt - 2);
;             const char* a1 = cA + (size_t)(t + 1) * kstep;
;             const char* a2 = last ? nA : cA + (size_t)(t + 2) * kstep; const char* b2 = last ? nB : cB + (size_t)(t + 2) * kstep;
;             const char* a3 = a2 + kstep; const char* b3 = b2 + kstep;
;     ...
;             PG8_LDB(B0, 1, 0); PG8_LDB(B1, 1, 1); PG8_SCHED; PG8_LDA(At, 1, 0); PG8_STAGE(PG8_SA(0, 1), a2 + hstep, voffA);
;             PG8_WAIT_V(8); PG8_WAIT_L(0); PG8_BAR; PG8_MMA(0, 0, At, B0); PG8_MMA(0, 1, At, B1); PG8_BAR; PG8_SCHED;
;             PG8_LDA(At, 1, 1); PG8_STAGE(PG8_SB(1, 0), b3, voffB); PG8_STAGE(PG8_SB(1, 1), b3 + hstep, voffB); PG8_STAGE(PG8_SA(1, 0), a3, voffA);
;             PG8_WAIT_V(8); PG8_WAIT_L(0); PG8_BAR; PG8_MMA(1, 0, At, B0); PG8_MMA(1, 1, At, B1); PG8_BAR; PG8_SCHED;
	s_add_i32 s79, 0, 0x18000
	s_add_i32 s80, 0, 0x1c000
	ds_read_b128 v[154:157], v219
	ds_read_b128 v[158:161], v220
	ds_read_b128 v[162:165], v219 offset:2048
	ds_read_b128 v[166:169], v220 offset:2048
	ds_read_b128 v[170:173], v221
	ds_read_b128 v[174:177], v222
	ds_read_b128 v[178:181], v221 offset:2048
	ds_read_b128 v[182:185], v222 offset:2048
	s_add_u32 s4, s50, 0x80000
	s_addc_u32 s5, s51, 0
	s_mov_b32 m0, s39
	s_nop 0
	global_load_lds_dwordx4 v130, s[50:51]
	s_mov_b32 m0, s59
	s_nop 0
	global_load_lds_dwordx4 v134, s[50:51]
	s_mov_b32 m0, s60
	ds_read_b128 v[186:189], v152 offset:32768
	ds_read_b128 v[190:193], v146 offset:32768
	ds_read_b128 v[194:197], v152 offset:34816
	ds_read_b128 v[198:201], v146 offset:34816
	ds_read_b128 v[202:205], v152 offset:36864
	ds_read_b128 v[206:209], v146 offset:36864
	ds_read_b128 v[210:213], v152 offset:38912
	ds_read_b128 v[214:217], v146 offset:38912
	global_load_lds_dwordx4 v130, s[4:5]
	s_mov_b32 m0, s61
	s_nop 0
	global_load_lds_dwordx4 v134, s[4:5]
	s_waitcnt vmcnt(8)
	s_waitcnt lgkmcnt(0)
	s_barrier
	s_setprio 1
	s_waitcnt lgkmcnt(0)
	v_mfma_f32_16x16x32_bf16 v[126:129], v[154:157], v[186:189], v[126:129]
	v_mfma_f32_16x16x32_bf16 v[122:125], v[162:165], v[186:189], v[122:125]
	v_mfma_f32_16x16x32_bf16 v[114:117], v[154:157], v[194:197], v[114:117]
	v_mfma_f32_16x16x32_bf16 v[106:109], v[162:165], v[194:197], v[106:109]
	v_mfma_f32_16x16x32_bf16 v[98:101], v[154:157], v[202:205], v[98:101]
	v_mfma_f32_16x16x32_bf16 v[90:93], v[162:165], v[202:205], v[90:93]
	v_mfma_f32_16x16x32_bf16 v[82:85], v[154:157], v[210:213], v[82:85]
	v_mfma_f32_16x16x32_bf16 v[74:77], v[162:165], v[210:213], v[74:77]
	v_mfma_f32_16x16x32_bf16 v[126:129], v[158:161], v[190:193], v[126:129]
	v_mfma_f32_16x16x32_bf16 v[122:125], v[166:169], v[190:193], v[122:125]
	v_mfma_f32_16x16x32_bf16 v[114:117], v[158:161], v[198:201], v[114:117]
	v_mfma_f32_16x16x32_bf16 v[106:109], v[166:169], v[198:201], v[106:109]
	v_mfma_f32_16x16x32_bf16 v[98:101], v[158:161], v[206:209], v[98:101]
	v_mfma_f32_16x16x32_bf16 v[90:93], v[166:169], v[206:209], v[90:93]
	v_mfma_f32_16x16x32_bf16 v[82:85], v[158:161], v[214:217], v[82:85]
	v_mfma_f32_16x16x32_bf16 v[74:77], v[166:169], v[214:217], v[74:77]
	s_setprio 0
	s_setprio 1
	v_mfma_f32_16x16x32_bf16 v[118:121], v[170:173], v[186:189], v[118:121]
	v_mfma_f32_16x16x32_bf16 v[110:113], v[178:181], v[186:189], v[110:113]
	v_mfma_f32_16x16x32_bf16 v[102:105], v[170:173], v[194:197], v[102:105]
	v_mfma_f32_16x16x32_bf16 v[94:97], v[178:181], v[194:197], v[94:97]
	v_mfma_f32_16x16x32_bf16 v[86:89], v[170:173], v[202:205], v[86:89]
	v_mfma_f32_16x16x32_bf16 v[78:81], v[178:181], v[202:205], v[78:81]
	v_mfma_f32_16x16x32_bf16 v[70:73], v[170:173], v[210:213], v[70:73]
	v_mfma_f32_16x16x32_bf16 v[66:69], v[178:181], v[210:213], v[66:69]
	v_mfma_f32_16x16x32_bf16 v[118:121], v[174:177], v[190:193], v[118:121]
	v_mfma_f32_16x16x32_bf16 v[110:113], v[182:185], v[190:193], v[110:113]
	v_mfma_f32_16x16x32_bf16 v[102:105], v[174:177], v[198:201], v[102:105]
	v_mfma_f32_16x16x32_bf16 v[94:97], v[182:185], v[198:201], v[94:97]
	v_mfma_f32_16x16x32_bf16 v[86:89], v[174:177], v[206:209], v[86:89]
	v_mfma_f32_16x16x32_bf16 v[78:81], v[182:185], v[206:209], v[78:81]
	v_mfma_f32_16x16x32_bf16 v[70:73], v[174:177], v[214:217], v[70:73]
	v_mfma_f32_16x16x32_bf16 v[66:69], v[182:185], v[214:217], v[66:69]
	s_setprio 0
	s_barrier
	s_add_i32 s4, s79, s58
	s_add_i32 m0, s4, 0xffffff80
	ds_read_b128 v[186:189], v152 offset:49152
	ds_read_b128 v[190:193], v146 offset:49152
	ds_read_b128 v[194:197], v152 offset:51200
	ds_read_b128 v[198:201], v146 offset:51200
	ds_read_b128 v[202:205], v152 offset:53248
	ds_read_b128 v[206:209], v146 offset:53248
	ds_read_b128 v[210:213], v152 offset:55296
	ds_read_b128 v[214:217], v146 offset:55296
	global_load_lds_dwordx4 v132, s[48:49] offset:128
	s_add_i32 m0, s4, 0x1f80
	s_add_u32 s4, s48, 0x80080
	s_addc_u32 s5, s49, 0
	global_load_lds_dwordx4 v136, s[48:49] offset:128
	s_add_i32 s48, s80, s58
	s_mov_b32 m0, s48
	s_nop 0
	global_load_lds_dwordx4 v132, s[4:5]
	s_add_i32 m0, s48, 0x2000
	s_nop 0
	global_load_lds_dwordx4 v136, s[4:5]
	s_waitcnt vmcnt(6)
	s_waitcnt lgkmcnt(0)
	s_barrier
	s_setprio 1
	s_waitcnt lgkmcnt(0)
	v_mfma_f32_16x16x32_bf16 v[62:65], v[154:157], v[186:189], v[62:65]
	v_mfma_f32_16x16x32_bf16 v[58:61], v[162:165], v[186:189], v[58:61]
	v_mfma_f32_16x16x32_bf16 v[50:53], v[154:157], v[194:197], v[50:53]
	v_mfma_f32_16x16x32_bf16 v[42:45], v[162:165], v[194:197], v[42:45]
	v_mfma_f32_16x16x32_bf16 v[34:37], v[154:157], v[202:205], v[34:37]
	v_mfma_f32_16x16x32_bf16 v[26:29], v[162:165], v[202:205], v[26:29]
	v_mfma_f32_16x16x32_bf16 v[18:21], v[154:157], v[210:213], v[18:21]
	v_mfma_f32_16x16x32_bf16 v[10:13], v[162:165], v[210:213], v[10:13]
	v_mfma_f32_16x16x32_bf16 v[62:65], v[158:161], v[190:193], v[62:65]
	v_mfma_f32_16x16x32_bf16 v[58:61], v[166:169], v[190:193], v[58:61]
	v_mfma_f32_16x16x32_bf16 v[50:53], v[158:161], v[198:201], v[50:53]
	v_mfma_f32_16x16x32_bf16 v[42:45], v[166:169], v[198:201], v[42:45]
	v_mfma_f32_16x16x32_bf16 v[34:37], v[158:161], v[206:209], v[34:37]
	v_mfma_f32_16x16x32_bf16 v[26:29], v[166:169], v[206:209], v[26:29]
	v_mfma_f32_16x16x32_bf16 v[18:21], v[158:161], v[214:217], v[18:21]
	v_mfma_f32_16x16x32_bf16 v[10:13], v[166:169], v[214:217], v[10:13]
	s_setprio 0
	s_setprio 1
	v_mfma_f32_16x16x32_bf16 v[54:57], v[170:173], v[186:189], v[54:57]
	v_mfma_f32_16x16x32_bf16 v[46:49], v[178:181], v[186:189], v[46:49]
	v_mfma_f32_16x16x32_bf16 v[38:41], v[170:173], v[194:197], v[38:41]
	v_mfma_f32_16x16x32_bf16 v[30:33], v[178:181], v[194:197], v[30:33]
	v_mfma_f32_16x16x32_bf16 v[22:25], v[170:173], v[202:205], v[22:25]
	v_mfma_f32_16x16x32_bf16 v[14:17], v[178:181], v[202:205], v[14:17]
	v_mfma_f32_16x16x32_bf16 v[6:9], v[170:173], v[210:213], v[6:9]
	v_mfma_f32_16x16x32_bf16 v[2:5], v[178:181], v[210:213], v[2:5]
	v_mfma_f32_16x16x32_bf16 v[54:57], v[174:177], v[190:193], v[54:57]
	v_mfma_f32_16x16x32_bf16 v[46:49], v[182:185], v[190:193], v[46:49]
	v_mfma_f32_16x16x32_bf16 v[38:41], v[174:177], v[198:201], v[38:41]
	v_mfma_f32_16x16x32_bf16 v[30:33], v[182:185], v[198:201], v[30:33]
	v_mfma_f32_16x16x32_bf16 v[22:25], v[174:177], v[206:209], v[22:25]
	v_mfma_f32_16x16x32_bf16 v[14:17], v[182:185], v[206:209], v[14:17]
	v_mfma_f32_16x16x32_bf16 v[6:9], v[174:177], v[214:217], v[6:9]
	v_mfma_f32_16x16x32_bf16 v[2:5], v[182:185], v[214:217], v[2:5]
	s_setprio 0
	s_barrier
	s_add_i32 s78, s78, 2
	s_add_u32 s40, s40, 0x100
	s_addc_u32 s41, s41, 0
	s_add_u32 s76, s76, 0x100
	s_addc_u32 s77, s77, 0
	s_cmp_gt_u32 s78, 29
	s_cbranch_scc0 .LBB0_763
	s_and_b64 vcc, exec, s[20:21]
	s_cbranch_vccz .LBB0_766
	s_barrier

; #define PG8_STAGE(bufoff, gbase, voff) do { _Pragma("unroll") for (int _i = 0; _i < 2; ++_i) \
;         __builtin_amdgcn_global_load_lds((const unsigned*)((const char*)(gbase) + (voff)[_i]), (PG8_LAS unsigned*)(lds + (bufoff) + ldsw + _i * 8192), 16, 0, 0); } while (0)
; #define PG8_LDA(dst, b, h) do { _Pragma("unroll") for (int m = 0; m < 4; ++m) _Pragma("unroll") for (int k = 0; k < 2; ++k) dst[m][k] = *(const PG8_LAS bf16x8*)(lds + PG8_SA(b, h) + aoff + m * 2048 + k * 1024); } while (0)
; #define PG8_LDB(dst, b, h) do { _Pragma("unroll") for (int n = 0; n < 2; ++n) _Pragma("unroll") for (int k = 0; k < 2; ++k) dst[n][k] = *(const PG8_LAS bf16x8*)(lds + PG8_SB(b, h) + boff + n * 2048 + k * 1024); } while (0)
; #define PG8_MMA(ai, bj, At, Bt) do { __builtin_amdgcn_s_setprio(1); _Pragma("unroll") for (int m = 0; m < 4; ++m) _Pragma("unroll") for (int n = 0; n < 2; ++n) _Pragma("unroll") for (int k = 0; k < 2; ++k) \
;         acc[ai][bj][m][n] = __builtin_amdgcn_mfma_f32_16x16x32_bf16(Bt[n][k], At[m][k], acc[ai][bj][m][n], 0, 0, 0); __builtin_amdgcn_s_setprio(0); } while (0)
; #define PG8_WAIT_V(n) asm volatile("s_waitcnt vmcnt(" #n ")" ::: "memory")
; #define PG8_WAIT_L(n) asm volatile("s_waitcnt lgkmcnt(" #n ")" ::: "memory")
; #define PG8_BAR __builtin_amdgcn_s_barrier()
; #define PG8_SCHED __builtin_amdgcn_sched_barrier(0)
; template <class Epi, class Sched, bool ALIGN_EPI = false, bool SP2 = false>
; __device__ __forceinline__ void gemm_phase(PG8_LAS unsigned char* lds, const Gemm g, const Sched& S, const Epi& E) {
;     ...
;             PG8_LDB(B0, 0, 0); PG8_LDB(B1, 0, 1); PG8_SCHED; PG8_LDA(At, 0, 0); PG8_STAGE(PG8_SA(1, 1), a1 + hstep, voffA);
;             PG8_WAIT_V(8); PG8_WAIT_L(0); PG8_BAR; PG8_MMA(0, 0, At, B0); PG8_MMA(0, 1, At, B1); PG8_BAR; PG8_SCHED;
;             PG8_LDA(At, 0, 1); PG8_STAGE(PG8_SB(0, 0), b2, voffB); PG8_STAGE(PG8_SB(0, 1), b2 + hstep, voffB); PG8_STAGE(PG8_SA(0, 0), a2, voffA);
;             PG8_WAIT_V(8); PG8_WAIT_L(0); PG8_BAR; PG8_MMA(1, 0, At, B0); PG8_MMA(1, 1, At, B1); PG8_BAR; PG8_SCHED;
.LBB0_913:
	ds_read_b128 v[156:159], v152
	ds_read_b128 v[160:163], v147
	ds_read_b128 v[164:167], v152 offset:2048
	ds_read_b128 v[168:171], v147 offset:2048
	ds_read_b128 v[172:175], v153
	ds_read_b128 v[176:179], v220
	ds_read_b128 v[180:183], v153 offset:2048
	ds_read_b128 v[184:187], v220 offset:2048
	s_add_u32 s4, s34, 0xfff80080
	s_addc_u32 s5, s35, -1
	s_cmp_eq_u32 s69, 28
	s_cselect_b32 s39, s25, s5
	s_cselect_b32 s38, s65, s4
	s_cselect_b32 s37, s23, s68
	s_cselect_b32 s36, s66, s67
	s_add_i32 m0, s53, 0x80
	s_nop 0
	global_load_lds_dwordx4 v136, s[4:5] offset:-128
	s_add_i32 m0, s58, 0x80
	s_nop 0
	global_load_lds_dwordx4 v132, s[4:5] offset:-128
	s_add_i32 m0, s31, 0xc000
	ds_read_b128 v[188:191], v154
	ds_read_b128 v[192:195], v146
	ds_read_b128 v[196:199], v154 offset:2048
	ds_read_b128 v[200:203], v146 offset:2048
	ds_read_b128 v[204:207], v154 offset:4096
	ds_read_b128 v[208:211], v146 offset:4096
	ds_read_b128 v[212:215], v154 offset:6144
	ds_read_b128 v[216:219], v146 offset:6144
	global_load_lds_dwordx4 v138, s[34:35]
	s_add_i32 m0, s31, 0xe000
	s_nop 0
	global_load_lds_dwordx4 v140, s[34:35]
	s_waitcnt vmcnt(8)
	s_waitcnt lgkmcnt(0)
	s_barrier
	s_setprio 1
	s_waitcnt lgkmcnt(0)
	v_mfma_f32_16x16x32_bf16 v[126:129], v[156:159], v[188:191], v[126:129]
	v_mfma_f32_16x16x32_bf16 v[122:125], v[164:167], v[188:191], v[122:125]
	v_mfma_f32_16x16x32_bf16 v[110:113], v[156:159], v[196:199], v[110:113]
	v_mfma_f32_16x16x32_bf16 v[106:109], v[164:167], v[196:199], v[106:109]
	v_mfma_f32_16x16x32_bf16 v[94:97], v[156:159], v[204:207], v[94:97]
	v_mfma_f32_16x16x32_bf16 v[90:93], v[164:167], v[204:207], v[90:93]
	v_mfma_f32_16x16x32_bf16 v[78:81], v[156:159], v[212:215], v[78:81]
	v_mfma_f32_16x16x32_bf16 v[74:77], v[164:167], v[212:215], v[74:77]
	v_mfma_f32_16x16x32_bf16 v[126:129], v[160:163], v[192:195], v[126:129]
	v_mfma_f32_16x16x32_bf16 v[122:125], v[168:171], v[192:195], v[122:125]
	v_mfma_f32_16x16x32_bf16 v[110:113], v[160:163], v[200:203], v[110:113]
	v_mfma_f32_16x16x32_bf16 v[106:109], v[168:171], v[200:203], v[106:109]
	v_mfma_f32_16x16x32_bf16 v[94:97], v[160:163], v[208:211], v[94:97]
	v_mfma_f32_16x16x32_bf16 v[90:93], v[168:171], v[208:211], v[90:93]
	v_mfma_f32_16x16x32_bf16 v[78:81], v[160:163], v[216:219], v[78:81]
	v_mfma_f32_16x16x32_bf16 v[74:77], v[168:171], v[216:219], v[74:77]
	s_setprio 0
	s_setprio 1
	v_mfma_f32_16x16x32_bf16 v[118:121], v[172:175], v[188:191], v[118:121]
	v_mfma_f32_16x16x32_bf16 v[114:117], v[180:183], v[188:191], v[114:117]
	v_mfma_f32_16x16x32_bf16 v[102:105], v[172:175], v[196:199], v[102:105]
	v_mfma_f32_16x16x32_bf16 v[98:101], v[180:183], v[196:199], v[98:101]
	v_mfma_f32_16x16x32_bf16 v[86:89], v[172:175], v[204:207], v[86:89]
	v_mfma_f32_16x16x32_bf16 v[82:85], v[180:183], v[204:207], v[82:85]
	v_mfma_f32_16x16x32_bf16 v[70:73], v[172:175], v[212:215], v[70:73]
	v_mfma_f32_16x16x32_bf16 v[66:69], v[180:183], v[212:215], v[66:69]
	v_mfma_f32_16x16x32_bf16 v[118:121], v[176:179], v[192:195], v[118:121]
	v_mfma_f32_16x16x32_bf16 v[114:117], v[184:187], v[192:195], v[114:117]
	v_mfma_f32_16x16x32_bf16 v[102:105], v[176:179], v[200:203], v[102:105]
	v_mfma_f32_16x16x32_bf16 v[98:101], v[184:187], v[200:203], v[98:101]
	v_mfma_f32_16x16x32_bf16 v[86:89], v[176:179], v[208:211], v[86:89]
	v_mfma_f32_16x16x32_bf16 v[82:85], v[184:187], v[208:211], v[82:85]
	v_mfma_f32_16x16x32_bf16 v[70:73], v[176:179], v[216:219], v[70:73]
	v_mfma_f32_16x16x32_bf16 v[66:69], v[184:187], v[216:219], v[66:69]
	s_setprio 0
	s_barrier
	s_add_i32 s4, s61, s40
	s_mov_b32 m0, s4
	ds_read_b128 v[188:191], v154 offset:16384
	ds_read_b128 v[192:195], v146 offset:16384
	ds_read_b128 v[196:199], v154 offset:18432
	ds_read_b128 v[200:203], v146 offset:18432
	ds_read_b128 v[204:207], v154 offset:20480
	ds_read_b128 v[208:211], v146 offset:20480
	ds_read_b128 v[212:215], v154 offset:22528
	ds_read_b128 v[216:219], v146 offset:22528
	global_load_lds_dwordx4 v134, s[36:37]
	s_add_i32 m0, s4, 0x2000
	s_add_u32 s4, s36, 0x80000
	s_addc_u32 s5, s37, 0
	s_add_i32 s70, s62, s40
	global_load_lds_dwordx4 v130, s[36:37]
	s_mov_b32 m0, s70
	s_nop 0
	global_load_lds_dwordx4 v134, s[4:5]
	s_add_i32 m0, s70, 0x2000
	s_nop 0
	global_load_lds_dwordx4 v130, s[4:5]
	s_waitcnt vmcnt(6)
	s_waitcnt lgkmcnt(0)
	s_barrier
	s_setprio 1
	s_waitcnt lgkmcnt(0)
	v_mfma_f32_16x16x32_bf16 v[62:65], v[156:159], v[188:191], v[62:65]
	v_mfma_f32_16x16x32_bf16 v[58:61], v[164:167], v[188:191], v[58:61]
	v_mfma_f32_16x16x32_bf16 v[46:49], v[156:159], v[196:199], v[46:49]
	v_mfma_f32_16x16x32_bf16 v[42:45], v[164:167], v[196:199], v[42:45]
	v_mfma_f32_16x16x32_bf16 v[30:33], v[156:159], v[204:207], v[30:33]
	v_mfma_f32_16x16x32_bf16 v[26:29], v[164:167], v[204:207], v[26:29]
	v_mfma_f32_16x16x32_bf16 v[14:17], v[156:159], v[212:215], v[14:17]
	v_mfma_f32_16x16x32_bf16 v[10:13], v[164:167], v[212:215], v[10:13]
	v_mfma_f32_16x16x32_bf16 v[62:65], v[160:163], v[192:195], v[62:65]
	v_mfma_f32_16x16x32_bf16 v[58:61], v[168:171], v[192:195], v[58:61]
	v_mfma_f32_16x16x32_bf16 v[46:49], v[160:163], v[200:203], v[46:49]
	v_mfma_f32_16x16x32_bf16 v[42:45], v[168:171], v[200:203], v[42:45]
	v_mfma_f32_16x16x32_bf16 v[30:33], v[160:163], v[208:211], v[30:33]
	v_mfma_f32_16x16x32_bf16 v[26:29], v[168:171], v[208:211], v[26:29]
	v_mfma_f32_16x16x32_bf16 v[14:17], v[160:163], v[216:219], v[14:17]
	v_mfma_f32_16x16x32_bf16 v[10:13], v[168:171], v[216:219], v[10:13]
	s_setprio 0
	s_setprio 1
	v_mfma_f32_16x16x32_bf16 v[54:57], v[172:175], v[188:191], v[54:57]
	v_mfma_f32_16x16x32_bf16 v[50:53], v[180:183], v[188:191], v[50:53]
	v_mfma_f32_16x16x32_bf16 v[38:41], v[172:175], v[196:199], v[38:41]
	v_mfma_f32_16x16x32_bf16 v[34:37], v[180:183], v[196:199], v[34:37]
	v_mfma_f32_16x16x32_bf16 v[22:25], v[172:175], v[204:207], v[22:25]
	v_mfma_f32_16x16x32_bf16 v[18:21], v[180:183], v[204:207], v[18:21]
	v_mfma_f32_16x16x32_bf16 v[6:9], v[172:175], v[212:215], v[6:9]
	v_mfma_f32_16x16x32_bf16 v[2:5], v[180:183], v[212:215], v[2:5]
	v_mfma_f32_16x16x32_bf16 v[54:57], v[176:179], v[192:195], v[54:57]
	v_mfma_f32_16x16x32_bf16 v[50:53], v[184:187], v[192:195], v[50:53]
	v_mfma_f32_16x16x32_bf16 v[38:41], v[176:179], v[200:203], v[38:41]
	v_mfma_f32_16x16x32_bf16 v[34:37], v[184:187], v[200:203], v[34:37]
	v_mfma_f32_16x16x32_bf16 v[22:25], v[176:179], v[208:211], v[22:25]
	v_mfma_f32_16x16x32_bf16 v[18:21], v[184:187], v[208:211], v[18:21]
	v_mfma_f32_16x16x32_bf16 v[6:9], v[176:179], v[216:219], v[6:9]
	v_mfma_f32_16x16x32_bf16 v[2:5], v[184:187], v[216:219], v[2:5]
	s_setprio 0
	s_barrier
; #define PG8_STAGE(bufoff, gbase, voff) do { _Pragma("unroll") for (int _i = 0; _i < 2; ++_i) \
;         __builtin_amdgcn_global_load_lds((const unsigned*)((const char*)(gbase) + (voff)[_i]), (PG8_LAS unsigned*)(lds + (bufoff) + ldsw + _i * 8192), 16, 0, 0); } while (0)
; #define PG8_LDA(dst, b, h) do { _Pragma("unroll") for (int m = 0; m < 4; ++m) _Pragma("unroll") for (int k = 0; k < 2; ++k) dst[m][k] = *(const PG8_LAS bf16x8*)(lds + PG8_SA(b, h) + aoff + m * 2048 + k * 1024); } while (0)
; #define PG8_LDB(dst, b, h) do { _Pragma("unroll") for (int n = 0; n < 2; ++n) _Pragma("unroll") for (int k = 0; k < 2; ++k) dst[n][k] = *(const PG8_LAS bf16x8*)(lds + PG8_SB(b, h) + boff + n * 2048 + k * 1024); } while (0)
; #define PG8_MMA(ai, bj, At, Bt) do { __builtin_amdgcn_s_setprio(1); _Pragma("unroll") for (int m = 0; m < 4; ++m) _Pragma("unroll") for (int n = 0; n < 2; ++n) _Pragma("unroll") for (int k = 0; k < 2; ++k) \
;         acc[ai][bj][m][n] = __builtin_amdgcn_mfma_f32_16x16x32_bf16(Bt[n][k], At[m][k], acc[ai][bj][m][n], 0, 0, 0); __builtin_amdgcn_s_setprio(0); } while (0)
; #define PG8_WAIT_V(n) asm volatile("s_waitcnt vmcnt(" #n ")" ::: "memory")
; #define PG8_WAIT_L(n) asm volatile("s_waitcnt lgkmcnt(" #n ")" ::: "memory")
; #define PG8_BAR __builtin_amdgcn_s_barrier()
; template <class Epi, class Sched, bool ALIGN_EPI = false, bool SP2 = false>
; __device__ __forceinline__ void gemm_phase(PG8_LAS unsigned char* lds, const Gemm g, const Sched& S, const Epi& E) {
;     ...
;         for (int t = 0; t < nt; t += 2) {
;             const bool last = (t == nt - 2);
;             const char* a1 = cA + (size_t)(t + 1) * kstep;
;             const char* a2 = last ? nA : cA + (size_t)(t + 2) * kstep; const char* b2 = last ? nB : cB + (size_t)(t + 2) * kstep;
;             const char* a3 = a2 + kstep; const char* b3 = b2 + kstep;
;     ...
;             PG8_LDB(B0, 1, 0); PG8_LDB(B1, 1, 1); PG8_SCHED; PG8_LDA(At, 1, 0); PG8_STAGE(PG8_SA(0, 1), a2 + hstep, voffA);
;             PG8_WAIT_V(8); PG8_WAIT_L(0); PG8_BAR; PG8_MMA(0, 0, At, B0); PG8_MMA(0, 1, At, B1); PG8_BAR; PG8_SCHED;
;             PG8_LDA(At, 1, 1); PG8_STAGE(PG8_SB(1, 0), b3, voffB); PG8_STAGE(PG8_SB(1, 1), b3 + hstep, voffB); PG8_STAGE(PG8_SA(1, 0), a3, voffA);
;             PG8_WAIT_V(8); PG8_WAIT_L(0); PG8_BAR; PG8_MMA(1, 0, At, B0); PG8_MMA(1, 1, At, B1); PG8_BAR; PG8_SCHED;
	s_add_i32 s70, 0, 0x18000
	s_add_i32 s71, 0, 0x1c000
	ds_read_b128 v[156:159], v221
	ds_read_b128 v[160:163], v222
	ds_read_b128 v[164:167], v221 offset:2048
	ds_read_b128 v[168:171], v222 offset:2048
	ds_read_b128 v[172:175], v223
	ds_read_b128 v[176:179], v224
	ds_read_b128 v[180:183], v223 offset:2048
	ds_read_b128 v[184:187], v224 offset:2048
	s_add_u32 s4, s38, 0x80000
	s_addc_u32 s5, s39, 0
	s_mov_b32 m0, s31
	s_nop 0
	global_load_lds_dwordx4 v136, s[38:39]
	s_mov_b32 m0, s49
	s_nop 0
	global_load_lds_dwordx4 v132, s[38:39]
	s_mov_b32 m0, s50
	ds_read_b128 v[188:191], v154 offset:32768
	ds_read_b128 v[192:195], v146 offset:32768
	ds_read_b128 v[196:199], v154 offset:34816
	ds_read_b128 v[200:203], v146 offset:34816
	ds_read_b128 v[204:207], v154 offset:36864
	ds_read_b128 v[208:211], v146 offset:36864
	ds_read_b128 v[212:215], v154 offset:38912
	ds_read_b128 v[216:219], v146 offset:38912
	global_load_lds_dwordx4 v136, s[4:5]
	s_mov_b32 m0, s51
	s_nop 0
	global_load_lds_dwordx4 v132, s[4:5]
	s_waitcnt vmcnt(8)
	s_waitcnt lgkmcnt(0)
	s_barrier
	s_setprio 1
	s_waitcnt lgkmcnt(0)
	v_mfma_f32_16x16x32_bf16 v[126:129], v[156:159], v[188:191], v[126:129]
	v_mfma_f32_16x16x32_bf16 v[122:125], v[164:167], v[188:191], v[122:125]
	v_mfma_f32_16x16x32_bf16 v[110:113], v[156:159], v[196:199], v[110:113]
	v_mfma_f32_16x16x32_bf16 v[106:109], v[164:167], v[196:199], v[106:109]
	v_mfma_f32_16x16x32_bf16 v[94:97], v[156:159], v[204:207], v[94:97]
	v_mfma_f32_16x16x32_bf16 v[90:93], v[164:167], v[204:207], v[90:93]
	v_mfma_f32_16x16x32_bf16 v[78:81], v[156:159], v[212:215], v[78:81]
	v_mfma_f32_16x16x32_bf16 v[74:77], v[164:167], v[212:215], v[74:77]
	v_mfma_f32_16x16x32_bf16 v[126:129], v[160:163], v[192:195], v[126:129]
	v_mfma_f32_16x16x32_bf16 v[122:125], v[168:171], v[192:195], v[122:125]
	v_mfma_f32_16x16x32_bf16 v[110:113], v[160:163], v[200:203], v[110:113]
	v_mfma_f32_16x16x32_bf16 v[106:109], v[168:171], v[200:203], v[106:109]
	v_mfma_f32_16x16x32_bf16 v[94:97], v[160:163], v[208:211], v[94:97]
	v_mfma_f32_16x16x32_bf16 v[90:93], v[168:171], v[208:211], v[90:93]
	v_mfma_f32_16x16x32_bf16 v[78:81], v[160:163], v[216:219], v[78:81]
	v_mfma_f32_16x16x32_bf16 v[74:77], v[168:171], v[216:219], v[74:77]
	s_setprio 0
	s_setprio 1
	v_mfma_f32_16x16x32_bf16 v[118:121], v[172:175], v[188:191], v[118:121]
	v_mfma_f32_16x16x32_bf16 v[114:117], v[180:183], v[188:191], v[114:117]
	v_mfma_f32_16x16x32_bf16 v[102:105], v[172:175], v[196:199], v[102:105]
	v_mfma_f32_16x16x32_bf16 v[98:101], v[180:183], v[196:199], v[98:101]
	v_mfma_f32_16x16x32_bf16 v[86:89], v[172:175], v[204:207], v[86:89]
	v_mfma_f32_16x16x32_bf16 v[82:85], v[180:183], v[204:207], v[82:85]
	v_mfma_f32_16x16x32_bf16 v[70:73], v[172:175], v[212:215], v[70:73]
	v_mfma_f32_16x16x32_bf16 v[66:69], v[180:183], v[212:215], v[66:69]
	v_mfma_f32_16x16x32_bf16 v[118:121], v[176:179], v[192:195], v[118:121]
	v_mfma_f32_16x16x32_bf16 v[114:117], v[184:187], v[192:195], v[114:117]
	v_mfma_f32_16x16x32_bf16 v[102:105], v[176:179], v[200:203], v[102:105]
	v_mfma_f32_16x16x32_bf16 v[98:101], v[184:187], v[200:203], v[98:101]
	v_mfma_f32_16x16x32_bf16 v[86:89], v[176:179], v[208:211], v[86:89]
	v_mfma_f32_16x16x32_bf16 v[82:85], v[184:187], v[208:211], v[82:85]
	v_mfma_f32_16x16x32_bf16 v[70:73], v[176:179], v[216:219], v[70:73]
	v_mfma_f32_16x16x32_bf16 v[66:69], v[184:187], v[216:219], v[66:69]
	s_setprio 0
	s_barrier
	s_add_i32 s4, s70, s40
	s_add_i32 m0, s4, 0xffffff80
	ds_read_b128 v[188:191], v154 offset:49152
	ds_read_b128 v[192:195], v146 offset:49152
	ds_read_b128 v[196:199], v154 offset:51200
	ds_read_b128 v[200:203], v146 offset:51200
	ds_read_b128 v[204:207], v154 offset:53248
	ds_read_b128 v[208:211], v146 offset:53248
	ds_read_b128 v[212:215], v154 offset:55296
	ds_read_b128 v[216:219], v146 offset:55296
	global_load_lds_dwordx4 v134, s[36:37] offset:128
	s_add_i32 m0, s4, 0x1f80
	s_add_u32 s4, s36, 0x80080
	s_addc_u32 s5, s37, 0
	global_load_lds_dwordx4 v130, s[36:37] offset:128
	s_add_i32 s36, s71, s40
	s_mov_b32 m0, s36
	s_nop 0
	global_load_lds_dwordx4 v134, s[4:5]
	s_add_i32 m0, s36, 0x2000
	s_nop 0
	global_load_lds_dwordx4 v130, s[4:5]
	s_waitcnt vmcnt(6)
	s_waitcnt lgkmcnt(0)
	s_barrier
	s_setprio 1
	s_waitcnt lgkmcnt(0)
	v_mfma_f32_16x16x32_bf16 v[62:65], v[156:159], v[188:191], v[62:65]
	v_mfma_f32_16x16x32_bf16 v[58:61], v[164:167], v[188:191], v[58:61]
	v_mfma_f32_16x16x32_bf16 v[46:49], v[156:159], v[196:199], v[46:49]
	v_mfma_f32_16x16x32_bf16 v[42:45], v[164:167], v[196:199], v[42:45]
	v_mfma_f32_16x16x32_bf16 v[30:33], v[156:159], v[204:207], v[30:33]
	v_mfma_f32_16x16x32_bf16 v[26:29], v[164:167], v[204:207], v[26:29]
	v_mfma_f32_16x16x32_bf16 v[14:17], v[156:159], v[212:215], v[14:17]
	v_mfma_f32_16x16x32_bf16 v[10:13], v[164:167], v[212:215], v[10:13]
	v_mfma_f32_16x16x32_bf16 v[62:65], v[160:163], v[192:195], v[62:65]
	v_mfma_f32_16x16x32_bf16 v[58:61], v[168:171], v[192:195], v[58:61]
	v_mfma_f32_16x16x32_bf16 v[46:49], v[160:163], v[200:203], v[46:49]
	v_mfma_f32_16x16x32_bf16 v[42:45], v[168:171], v[200:203], v[42:45]
	v_mfma_f32_16x16x32_bf16 v[30:33], v[160:163], v[208:211], v[30:33]
	v_mfma_f32_16x16x32_bf16 v[26:29], v[168:171], v[208:211], v[26:29]
	v_mfma_f32_16x16x32_bf16 v[14:17], v[160:163], v[216:219], v[14:17]
	v_mfma_f32_16x16x32_bf16 v[10:13], v[168:171], v[216:219], v[10:13]
	s_setprio 0
	s_setprio 1
	v_mfma_f32_16x16x32_bf16 v[54:57], v[172:175], v[188:191], v[54:57]
	v_mfma_f32_16x16x32_bf16 v[50:53], v[180:183], v[188:191], v[50:53]
	v_mfma_f32_16x16x32_bf16 v[38:41], v[172:175], v[196:199], v[38:41]
	v_mfma_f32_16x16x32_bf16 v[34:37], v[180:183], v[196:199], v[34:37]
	v_mfma_f32_16x16x32_bf16 v[22:25], v[172:175], v[204:207], v[22:25]
	v_mfma_f32_16x16x32_bf16 v[18:21], v[180:183], v[204:207], v[18:21]
	v_mfma_f32_16x16x32_bf16 v[6:9], v[172:175], v[212:215], v[6:9]
	v_mfma_f32_16x16x32_bf16 v[2:5], v[180:183], v[212:215], v[2:5]
	v_mfma_f32_16x16x32_bf16 v[54:57], v[176:179], v[192:195], v[54:57]
	v_mfma_f32_16x16x32_bf16 v[50:53], v[184:187], v[192:195], v[50:53]
	v_mfma_f32_16x16x32_bf16 v[38:41], v[176:179], v[200:203], v[38:41]
	v_mfma_f32_16x16x32_bf16 v[34:37], v[184:187], v[200:203], v[34:37]
	v_mfma_f32_16x16x32_bf16 v[22:25], v[176:179], v[208:211], v[22:25]
	v_mfma_f32_16x16x32_bf16 v[18:21], v[184:187], v[208:211], v[18:21]
	v_mfma_f32_16x16x32_bf16 v[6:9], v[176:179], v[216:219], v[6:9]
	v_mfma_f32_16x16x32_bf16 v[2:5], v[184:187], v[216:219], v[2:5]
	s_setprio 0
	s_barrier
	s_add_i32 s69, s69, 2
	s_add_u32 s34, s34, 0x100
	s_addc_u32 s35, s35, 0
	s_add_u32 s67, s67, 0x100
	s_addc_u32 s68, s68, 0
	s_cmp_gt_u32 s69, 29
	s_cbranch_scc0 .LBB0_913
	s_and_b64 vcc, exec, s[20:21]
	s_cbranch_vccz .LBB0_916
	s_barrier

; #define PG8_STAGE(bufoff, gbase, voff) do { _Pragma("unroll") for (int _i = 0; _i < 2; ++_i) \
;         __builtin_amdgcn_global_load_lds((const unsigned*)((const char*)(gbase) + (voff)[_i]), (PG8_LAS unsigned*)(lds + (bufoff) + ldsw + _i * 8192), 16, 0, 0); } while (0)
; #define PG8_LDA(dst, b, h) do { _Pragma("unroll") for (int m = 0; m < 4; ++m) _Pragma("unroll") for (int k = 0; k < 2; ++k) dst[m][k] = *(const PG8_LAS bf16x8*)(lds + PG8_SA(b, h) + aoff + m * 2048 + k * 1024); } while (0)
; #define PG8_LDB(dst, b, h) do { _Pragma("unroll") for (int n = 0; n < 2; ++n) _Pragma("unroll") for (int k = 0; k < 2; ++k) dst[n][k] = *(const PG8_LAS bf16x8*)(lds + PG8_SB(b, h) + boff + n * 2048 + k * 1024); } while (0)
; #define PG8_MMA(ai, bj, At, Bt) do { __builtin_amdgcn_s_setprio(1); _Pragma("unroll") for (int m = 0; m < 4; ++m) _Pragma("unroll") for (int n = 0; n < 2; ++n) _Pragma("unroll") for (int k = 0; k < 2; ++k) \
;         acc[ai][bj][m][n] = __builtin_amdgcn_mfma_f32_16x16x32_bf16(Bt[n][k], At[m][k], acc[ai][bj][m][n], 0, 0, 0); __builtin_amdgcn_s_setprio(0); } while (0)
; #define PG8_WAIT_V(n) asm volatile("s_waitcnt vmcnt(" #n ")" ::: "memory")
; #define PG8_WAIT_L(n) asm volatile("s_waitcnt lgkmcnt(" #n ")" ::: "memory")
; #define PG8_BAR __builtin_amdgcn_s_barrier()
; #define PG8_SCHED __builtin_amdgcn_sched_barrier(0)
; template <class Epi, class Sched, bool ALIGN_EPI = false, bool SP2 = false>
; __device__ __forceinline__ void gemm_phase(PG8_LAS unsigned char* lds, const Gemm g, const Sched& S, const Epi& E) {
;     ...
;             PG8_LDB(B0, 0, 0); PG8_LDB(B1, 0, 1); PG8_SCHED; PG8_LDA(At, 0, 0); PG8_STAGE(PG8_SA(1, 1), a1 + hstep, voffA);
;             PG8_WAIT_V(8); PG8_WAIT_L(0); PG8_BAR; PG8_MMA(0, 0, At, B0); PG8_MMA(0, 1, At, B1); PG8_BAR; PG8_SCHED;
;             PG8_LDA(At, 0, 1); PG8_STAGE(PG8_SB(0, 0), b2, voffB); PG8_STAGE(PG8_SB(0, 1), b2 + hstep, voffB); PG8_STAGE(PG8_SA(0, 0), a2, voffA);
;             PG8_WAIT_V(8); PG8_WAIT_L(0); PG8_BAR; PG8_MMA(1, 0, At, B0); PG8_MMA(1, 1, At, B1); PG8_BAR; PG8_SCHED;
.LBB0_1017:
	ds_read_b128 v[154:157], v150
	ds_read_b128 v[158:161], v147
	ds_read_b128 v[162:165], v150 offset:2048
	ds_read_b128 v[166:169], v147 offset:2048
	ds_read_b128 v[170:173], v151
	ds_read_b128 v[174:177], v218
	ds_read_b128 v[178:181], v151 offset:2048
	ds_read_b128 v[182:185], v218 offset:2048
	s_add_u32 s34, s30, 0x100
	s_addc_u32 s35, s31, 0
	s_cmpk_eq_i32 s74, 0x54
	s_cselect_b32 s39, s9, s35
	s_cselect_b32 s38, s8, s34
	s_cselect_b32 s37, s29, s73
	s_cselect_b32 s36, s28, s72
	s_add_i32 m0, s58, 0x80
	s_nop 0
	global_load_lds_dwordx4 v130, s[34:35] offset:-128
	s_add_i32 m0, s59, 0x80
	s_nop 0
	global_load_lds_dwordx4 v134, s[34:35] offset:-128
	s_add_i32 m0, s49, 0xc000
	ds_read_b128 v[186:189], v152
	ds_read_b128 v[190:193], v146
	ds_read_b128 v[194:197], v152 offset:2048
	ds_read_b128 v[198:201], v146 offset:2048
	ds_read_b128 v[202:205], v152 offset:4096
	ds_read_b128 v[206:209], v146 offset:4096
	ds_read_b128 v[210:213], v152 offset:6144
	ds_read_b128 v[214:217], v146 offset:6144
	global_load_lds_dwordx4 v138, s[30:31]
	s_add_i32 m0, s49, 0xe000
	s_nop 0
	global_load_lds_dwordx4 v140, s[30:31]
	s_waitcnt vmcnt(8)
	s_waitcnt lgkmcnt(0)
	s_barrier
	s_setprio 1
	s_waitcnt lgkmcnt(0)
	v_mfma_f32_16x16x32_bf16 v[126:129], v[154:157], v[186:189], v[126:129]
	v_mfma_f32_16x16x32_bf16 v[122:125], v[162:165], v[186:189], v[122:125]
	v_mfma_f32_16x16x32_bf16 v[114:117], v[154:157], v[194:197], v[114:117]
	v_mfma_f32_16x16x32_bf16 v[106:109], v[162:165], v[194:197], v[106:109]
	v_mfma_f32_16x16x32_bf16 v[98:101], v[154:157], v[202:205], v[98:101]
	v_mfma_f32_16x16x32_bf16 v[90:93], v[162:165], v[202:205], v[90:93]
	v_mfma_f32_16x16x32_bf16 v[82:85], v[154:157], v[210:213], v[82:85]
	v_mfma_f32_16x16x32_bf16 v[74:77], v[162:165], v[210:213], v[74:77]
	v_mfma_f32_16x16x32_bf16 v[126:129], v[158:161], v[190:193], v[126:129]
	v_mfma_f32_16x16x32_bf16 v[122:125], v[166:169], v[190:193], v[122:125]
	v_mfma_f32_16x16x32_bf16 v[114:117], v[158:161], v[198:201], v[114:117]
	v_mfma_f32_16x16x32_bf16 v[106:109], v[166:169], v[198:201], v[106:109]
	v_mfma_f32_16x16x32_bf16 v[98:101], v[158:161], v[206:209], v[98:101]
	v_mfma_f32_16x16x32_bf16 v[90:93], v[166:169], v[206:209], v[90:93]
	v_mfma_f32_16x16x32_bf16 v[82:85], v[158:161], v[214:217], v[82:85]
	v_mfma_f32_16x16x32_bf16 v[74:77], v[166:169], v[214:217], v[74:77]
	s_setprio 0
	s_setprio 1
	v_mfma_f32_16x16x32_bf16 v[118:121], v[170:173], v[186:189], v[118:121]
	v_mfma_f32_16x16x32_bf16 v[110:113], v[178:181], v[186:189], v[110:113]
	v_mfma_f32_16x16x32_bf16 v[102:105], v[170:173], v[194:197], v[102:105]
	v_mfma_f32_16x16x32_bf16 v[94:97], v[178:181], v[194:197], v[94:97]
	v_mfma_f32_16x16x32_bf16 v[86:89], v[170:173], v[202:205], v[86:89]
	v_mfma_f32_16x16x32_bf16 v[78:81], v[178:181], v[202:205], v[78:81]
	v_mfma_f32_16x16x32_bf16 v[70:73], v[170:173], v[210:213], v[70:73]
	v_mfma_f32_16x16x32_bf16 v[66:69], v[178:181], v[210:213], v[66:69]
	v_mfma_f32_16x16x32_bf16 v[118:121], v[174:177], v[190:193], v[118:121]
	v_mfma_f32_16x16x32_bf16 v[110:113], v[182:185], v[190:193], v[110:113]
	v_mfma_f32_16x16x32_bf16 v[102:105], v[174:177], v[198:201], v[102:105]
	v_mfma_f32_16x16x32_bf16 v[94:97], v[182:185], v[198:201], v[94:97]
	v_mfma_f32_16x16x32_bf16 v[86:89], v[174:177], v[206:209], v[86:89]
	v_mfma_f32_16x16x32_bf16 v[78:81], v[182:185], v[206:209], v[78:81]
	v_mfma_f32_16x16x32_bf16 v[70:73], v[174:177], v[214:217], v[70:73]
	v_mfma_f32_16x16x32_bf16 v[66:69], v[182:185], v[214:217], v[66:69]
	s_setprio 0
	s_barrier
	s_add_i32 s4, s62, s48
	s_mov_b32 m0, s4
	ds_read_b128 v[186:189], v152 offset:16384
	ds_read_b128 v[190:193], v146 offset:16384
	ds_read_b128 v[194:197], v152 offset:18432
	ds_read_b128 v[198:201], v146 offset:18432
	ds_read_b128 v[202:205], v152 offset:20480
	ds_read_b128 v[206:209], v146 offset:20480
	ds_read_b128 v[210:213], v152 offset:22528
	ds_read_b128 v[214:217], v146 offset:22528
	global_load_lds_dwordx4 v132, s[36:37]
	s_add_i32 m0, s4, 0x2000
	s_add_u32 s4, s36, 0x160000
	s_addc_u32 s5, s37, 0
	s_add_i32 s30, s63, s48
	global_load_lds_dwordx4 v136, s[36:37]
	s_mov_b32 m0, s30
	s_nop 0
	global_load_lds_dwordx4 v132, s[4:5]
	s_add_i32 m0, s30, 0x2000
	s_nop 0
	global_load_lds_dwordx4 v136, s[4:5]
	s_waitcnt vmcnt(6)
	s_waitcnt lgkmcnt(0)
	s_barrier
	s_setprio 1
	s_waitcnt lgkmcnt(0)
	v_mfma_f32_16x16x32_bf16 v[62:65], v[154:157], v[186:189], v[62:65]
	v_mfma_f32_16x16x32_bf16 v[58:61], v[162:165], v[186:189], v[58:61]
	v_mfma_f32_16x16x32_bf16 v[50:53], v[154:157], v[194:197], v[50:53]
	v_mfma_f32_16x16x32_bf16 v[42:45], v[162:165], v[194:197], v[42:45]
	v_mfma_f32_16x16x32_bf16 v[34:37], v[154:157], v[202:205], v[34:37]
	v_mfma_f32_16x16x32_bf16 v[26:29], v[162:165], v[202:205], v[26:29]
	v_mfma_f32_16x16x32_bf16 v[18:21], v[154:157], v[210:213], v[18:21]
	v_mfma_f32_16x16x32_bf16 v[10:13], v[162:165], v[210:213], v[10:13]
	v_mfma_f32_16x16x32_bf16 v[62:65], v[158:161], v[190:193], v[62:65]
	v_mfma_f32_16x16x32_bf16 v[58:61], v[166:169], v[190:193], v[58:61]
	v_mfma_f32_16x16x32_bf16 v[50:53], v[158:161], v[198:201], v[50:53]
	v_mfma_f32_16x16x32_bf16 v[42:45], v[166:169], v[198:201], v[42:45]
	v_mfma_f32_16x16x32_bf16 v[34:37], v[158:161], v[206:209], v[34:37]
	v_mfma_f32_16x16x32_bf16 v[26:29], v[166:169], v[206:209], v[26:29]
	v_mfma_f32_16x16x32_bf16 v[18:21], v[158:161], v[214:217], v[18:21]
	v_mfma_f32_16x16x32_bf16 v[10:13], v[166:169], v[214:217], v[10:13]
	s_setprio 0
	s_setprio 1
	v_mfma_f32_16x16x32_bf16 v[54:57], v[170:173], v[186:189], v[54:57]
	v_mfma_f32_16x16x32_bf16 v[46:49], v[178:181], v[186:189], v[46:49]
	v_mfma_f32_16x16x32_bf16 v[38:41], v[170:173], v[194:197], v[38:41]
	v_mfma_f32_16x16x32_bf16 v[30:33], v[178:181], v[194:197], v[30:33]
	v_mfma_f32_16x16x32_bf16 v[22:25], v[170:173], v[202:205], v[22:25]
	v_mfma_f32_16x16x32_bf16 v[14:17], v[178:181], v[202:205], v[14:17]
	v_mfma_f32_16x16x32_bf16 v[6:9], v[170:173], v[210:213], v[6:9]
	v_mfma_f32_16x16x32_bf16 v[2:5], v[178:181], v[210:213], v[2:5]
	v_mfma_f32_16x16x32_bf16 v[54:57], v[174:177], v[190:193], v[54:57]
	v_mfma_f32_16x16x32_bf16 v[46:49], v[182:185], v[190:193], v[46:49]
	v_mfma_f32_16x16x32_bf16 v[38:41], v[174:177], v[198:201], v[38:41]
	v_mfma_f32_16x16x32_bf16 v[30:33], v[182:185], v[198:201], v[30:33]
	v_mfma_f32_16x16x32_bf16 v[22:25], v[174:177], v[206:209], v[22:25]
	v_mfma_f32_16x16x32_bf16 v[14:17], v[182:185], v[206:209], v[14:17]
	v_mfma_f32_16x16x32_bf16 v[6:9], v[174:177], v[214:217], v[6:9]
	v_mfma_f32_16x16x32_bf16 v[2:5], v[182:185], v[214:217], v[2:5]
	s_setprio 0
	s_barrier
; #define PG8_STAGE(bufoff, gbase, voff) do { _Pragma("unroll") for (int _i = 0; _i < 2; ++_i) \
;         __builtin_amdgcn_global_load_lds((const unsigned*)((const char*)(gbase) + (voff)[_i]), (PG8_LAS unsigned*)(lds + (bufoff) + ldsw + _i * 8192), 16, 0, 0); } while (0)
; #define PG8_LDA(dst, b, h) do { _Pragma("unroll") for (int m = 0; m < 4; ++m) _Pragma("unroll") for (int k = 0; k < 2; ++k) dst[m][k] = *(const PG8_LAS bf16x8*)(lds + PG8_SA(b, h) + aoff + m * 2048 + k * 1024); } while (0)
; #define PG8_LDB(dst, b, h) do { _Pragma("unroll") for (int n = 0; n < 2; ++n) _Pragma("unroll") for (int k = 0; k < 2; ++k) dst[n][k] = *(const PG8_LAS bf16x8*)(lds + PG8_SB(b, h) + boff + n * 2048 + k * 1024); } while (0)
; #define PG8_MMA(ai, bj, At, Bt) do { __builtin_amdgcn_s_setprio(1); _Pragma("unroll") for (int m = 0; m < 4; ++m) _Pragma("unroll") for (int n = 0; n < 2; ++n) _Pragma("unroll") for (int k = 0; k < 2; ++k) \
;         acc[ai][bj][m][n] = __builtin_amdgcn_mfma_f32_16x16x32_bf16(Bt[n][k], At[m][k], acc[ai][bj][m][n], 0, 0, 0); __builtin_amdgcn_s_setprio(0); } while (0)
; #define PG8_WAIT_V(n) asm volatile("s_waitcnt vmcnt(" #n ")" ::: "memory")
; #define PG8_WAIT_L(n) asm volatile("s_waitcnt lgkmcnt(" #n ")" ::: "memory")
; #define PG8_BAR __builtin_amdgcn_s_barrier()
; #define PG8_SCHED __builtin_amdgcn_sched_barrier(0)
; template <class Epi, class Sched, bool ALIGN_EPI = false, bool SP2 = false>
; __device__ __forceinline__ void gemm_phase(PG8_LAS unsigned char* lds, const Gemm g, const Sched& S, const Epi& E) {
;     ...
;         for (int t = 0; t < nt; t += 2) {
;             const bool last = (t == nt - 2);
;     ...
;             PG8_LDB(B0, 1, 0); PG8_LDB(B1, 1, 1); PG8_SCHED; PG8_LDA(At, 1, 0); PG8_STAGE(PG8_SA(0, 1), a2 + hstep, voffA);
;             PG8_WAIT_V(8); PG8_WAIT_L(0); PG8_BAR; PG8_MMA(0, 0, At, B0); PG8_MMA(0, 1, At, B1); PG8_BAR; PG8_SCHED;
;             PG8_LDA(At, 1, 1); PG8_STAGE(PG8_SB(1, 0), b3, voffB); PG8_STAGE(PG8_SB(1, 1), b3 + hstep, voffB); PG8_STAGE(PG8_SA(1, 0), a3, voffA);
;             PG8_WAIT_V(8); PG8_WAIT_L(0); PG8_BAR; PG8_MMA(1, 0, At, B0); PG8_MMA(1, 1, At, B1); PG8_BAR; PG8_SCHED;
	s_add_i32 s30, 0, 0x18000
	s_add_i32 s31, 0, 0x1c000
	ds_read_b128 v[154:157], v219
	ds_read_b128 v[158:161], v220
	ds_read_b128 v[162:165], v219 offset:2048
	ds_read_b128 v[166:169], v220 offset:2048
	ds_read_b128 v[170:173], v221
	ds_read_b128 v[174:177], v222
	ds_read_b128 v[178:181], v221 offset:2048
	ds_read_b128 v[182:185], v222 offset:2048
	s_add_u32 s4, s38, 0x160000
	s_addc_u32 s5, s39, 0
	s_mov_b32 m0, s49
	s_nop 0
	global_load_lds_dwordx4 v130, s[38:39]
	s_mov_b32 m0, s50
	s_nop 0
	global_load_lds_dwordx4 v134, s[38:39]
	s_mov_b32 m0, s51
	ds_read_b128 v[186:189], v152 offset:32768
	ds_read_b128 v[190:193], v146 offset:32768
	ds_read_b128 v[194:197], v152 offset:34816
	ds_read_b128 v[198:201], v146 offset:34816
	ds_read_b128 v[202:205], v152 offset:36864
	ds_read_b128 v[206:209], v146 offset:36864
	ds_read_b128 v[210:213], v152 offset:38912
	ds_read_b128 v[214:217], v146 offset:38912
	global_load_lds_dwordx4 v130, s[4:5]
	s_mov_b32 m0, s52
	s_nop 0
	global_load_lds_dwordx4 v134, s[4:5]
	s_waitcnt vmcnt(8)
	s_waitcnt lgkmcnt(0)
	s_barrier
	s_setprio 1
	s_waitcnt lgkmcnt(0)
	v_mfma_f32_16x16x32_bf16 v[126:129], v[154:157], v[186:189], v[126:129]
	v_mfma_f32_16x16x32_bf16 v[122:125], v[162:165], v[186:189], v[122:125]
	v_mfma_f32_16x16x32_bf16 v[114:117], v[154:157], v[194:197], v[114:117]
	v_mfma_f32_16x16x32_bf16 v[106:109], v[162:165], v[194:197], v[106:109]
	v_mfma_f32_16x16x32_bf16 v[98:101], v[154:157], v[202:205], v[98:101]
	v_mfma_f32_16x16x32_bf16 v[90:93], v[162:165], v[202:205], v[90:93]
	v_mfma_f32_16x16x32_bf16 v[82:85], v[154:157], v[210:213], v[82:85]
	v_mfma_f32_16x16x32_bf16 v[74:77], v[162:165], v[210:213], v[74:77]
	v_mfma_f32_16x16x32_bf16 v[126:129], v[158:161], v[190:193], v[126:129]
	v_mfma_f32_16x16x32_bf16 v[122:125], v[166:169], v[190:193], v[122:125]
	v_mfma_f32_16x16x32_bf16 v[114:117], v[158:161], v[198:201], v[114:117]
	v_mfma_f32_16x16x32_bf16 v[106:109], v[166:169], v[198:201], v[106:109]
	v_mfma_f32_16x16x32_bf16 v[98:101], v[158:161], v[206:209], v[98:101]
	v_mfma_f32_16x16x32_bf16 v[90:93], v[166:169], v[206:209], v[90:93]
	v_mfma_f32_16x16x32_bf16 v[82:85], v[158:161], v[214:217], v[82:85]
	v_mfma_f32_16x16x32_bf16 v[74:77], v[166:169], v[214:217], v[74:77]
	s_setprio 0
	s_setprio 1
	v_mfma_f32_16x16x32_bf16 v[118:121], v[170:173], v[186:189], v[118:121]
	v_mfma_f32_16x16x32_bf16 v[110:113], v[178:181], v[186:189], v[110:113]
	v_mfma_f32_16x16x32_bf16 v[102:105], v[170:173], v[194:197], v[102:105]
	v_mfma_f32_16x16x32_bf16 v[94:97], v[178:181], v[194:197], v[94:97]
	v_mfma_f32_16x16x32_bf16 v[86:89], v[170:173], v[202:205], v[86:89]
	v_mfma_f32_16x16x32_bf16 v[78:81], v[178:181], v[202:205], v[78:81]
	v_mfma_f32_16x16x32_bf16 v[70:73], v[170:173], v[210:213], v[70:73]
	v_mfma_f32_16x16x32_bf16 v[66:69], v[178:181], v[210:213], v[66:69]
	v_mfma_f32_16x16x32_bf16 v[118:121], v[174:177], v[190:193], v[118:121]
	v_mfma_f32_16x16x32_bf16 v[110:113], v[182:185], v[190:193], v[110:113]
	v_mfma_f32_16x16x32_bf16 v[102:105], v[174:177], v[198:201], v[102:105]
	v_mfma_f32_16x16x32_bf16 v[94:97], v[182:185], v[198:201], v[94:97]
	v_mfma_f32_16x16x32_bf16 v[86:89], v[174:177], v[206:209], v[86:89]
	v_mfma_f32_16x16x32_bf16 v[78:81], v[182:185], v[206:209], v[78:81]
	v_mfma_f32_16x16x32_bf16 v[70:73], v[174:177], v[214:217], v[70:73]
	v_mfma_f32_16x16x32_bf16 v[66:69], v[182:185], v[214:217], v[66:69]
	s_setprio 0
	s_barrier
	s_add_i32 s4, s30, s48
	s_add_i32 m0, s4, 0xffffff80
	ds_read_b128 v[186:189], v152 offset:49152
	ds_read_b128 v[190:193], v146 offset:49152
	ds_read_b128 v[194:197], v152 offset:51200
	ds_read_b128 v[198:201], v146 offset:51200
	ds_read_b128 v[202:205], v152 offset:53248
	ds_read_b128 v[206:209], v146 offset:53248
	ds_read_b128 v[210:213], v152 offset:55296
	ds_read_b128 v[214:217], v146 offset:55296
	global_load_lds_dwordx4 v132, s[36:37] offset:128
	s_add_i32 m0, s4, 0x1f80
	s_add_u32 s4, s36, 0x160080
	s_addc_u32 s5, s37, 0
	s_add_i32 s30, s31, s48
	global_load_lds_dwordx4 v136, s[36:37] offset:128
	s_mov_b32 m0, s30
	s_nop 0
	global_load_lds_dwordx4 v132, s[4:5]
	s_add_i32 m0, s30, 0x2000
	s_nop 0
	global_load_lds_dwordx4 v136, s[4:5]
	s_waitcnt vmcnt(6)
	s_waitcnt lgkmcnt(0)
	s_barrier
	s_setprio 1
	s_waitcnt lgkmcnt(0)
	v_mfma_f32_16x16x32_bf16 v[62:65], v[154:157], v[186:189], v[62:65]
	v_mfma_f32_16x16x32_bf16 v[58:61], v[162:165], v[186:189], v[58:61]
	v_mfma_f32_16x16x32_bf16 v[50:53], v[154:157], v[194:197], v[50:53]
	v_mfma_f32_16x16x32_bf16 v[42:45], v[162:165], v[194:197], v[42:45]
	v_mfma_f32_16x16x32_bf16 v[34:37], v[154:157], v[202:205], v[34:37]
	v_mfma_f32_16x16x32_bf16 v[26:29], v[162:165], v[202:205], v[26:29]
	v_mfma_f32_16x16x32_bf16 v[18:21], v[154:157], v[210:213], v[18:21]
	v_mfma_f32_16x16x32_bf16 v[10:13], v[162:165], v[210:213], v[10:13]
	v_mfma_f32_16x16x32_bf16 v[62:65], v[158:161], v[190:193], v[62:65]
	v_mfma_f32_16x16x32_bf16 v[58:61], v[166:169], v[190:193], v[58:61]
	v_mfma_f32_16x16x32_bf16 v[50:53], v[158:161], v[198:201], v[50:53]
	v_mfma_f32_16x16x32_bf16 v[42:45], v[166:169], v[198:201], v[42:45]
	v_mfma_f32_16x16x32_bf16 v[34:37], v[158:161], v[206:209], v[34:37]
	v_mfma_f32_16x16x32_bf16 v[26:29], v[166:169], v[206:209], v[26:29]
	v_mfma_f32_16x16x32_bf16 v[18:21], v[158:161], v[214:217], v[18:21]
	v_mfma_f32_16x16x32_bf16 v[10:13], v[166:169], v[214:217], v[10:13]
	s_setprio 0
	s_setprio 1
	v_mfma_f32_16x16x32_bf16 v[54:57], v[170:173], v[186:189], v[54:57]
	v_mfma_f32_16x16x32_bf16 v[46:49], v[178:181], v[186:189], v[46:49]
	v_mfma_f32_16x16x32_bf16 v[38:41], v[170:173], v[194:197], v[38:41]
	v_mfma_f32_16x16x32_bf16 v[30:33], v[178:181], v[194:197], v[30:33]
	v_mfma_f32_16x16x32_bf16 v[22:25], v[170:173], v[202:205], v[22:25]
	v_mfma_f32_16x16x32_bf16 v[14:17], v[178:181], v[202:205], v[14:17]
	v_mfma_f32_16x16x32_bf16 v[6:9], v[170:173], v[210:213], v[6:9]
	v_mfma_f32_16x16x32_bf16 v[2:5], v[178:181], v[210:213], v[2:5]
	v_mfma_f32_16x16x32_bf16 v[54:57], v[174:177], v[190:193], v[54:57]
	v_mfma_f32_16x16x32_bf16 v[46:49], v[182:185], v[190:193], v[46:49]
	v_mfma_f32_16x16x32_bf16 v[38:41], v[174:177], v[198:201], v[38:41]
	v_mfma_f32_16x16x32_bf16 v[30:33], v[182:185], v[198:201], v[30:33]
	v_mfma_f32_16x16x32_bf16 v[22:25], v[174:177], v[206:209], v[22:25]
	v_mfma_f32_16x16x32_bf16 v[14:17], v[182:185], v[206:209], v[14:17]
	v_mfma_f32_16x16x32_bf16 v[6:9], v[174:177], v[214:217], v[6:9]
	v_mfma_f32_16x16x32_bf16 v[2:5], v[182:185], v[214:217], v[2:5]
	s_setprio 0
	s_barrier
	s_add_i32 s74, s74, 2
	s_add_u32 s72, s72, 0x100
	s_addc_u32 s73, s73, 0
	s_cmpk_gt_u32 s74, 0x55
	s_mov_b64 s[30:31], s[34:35]
	s_cbranch_scc0 .LBB0_1017
	s_and_b64 vcc, exec, s[18:19]
	s_cbranch_vccz .LBB0_1020
	s_barrier
